# baseline (speedup 1.0000x reference)
; template <int EPI, int PN>
; __device__ void gemm_phase(const Params& p, const u16* __restrict__ A, const u16* __restrict__ Bt, int nNt, char* smem) {
;     ...
;     for (int kt = 0; kt < 32; ++kt) {
;       asm volatile("s_waitcnt vmcnt(0)" ::: "memory");
;       __builtin_amdgcn_s_barrier();
;       const u16* Ab = ring + (kt & 1) * STG;
;       const u16* Bb = Ab + 16384;
;       u16* st = ring + ((kt + 1) & 1) * STG;
;       const bool pre = (kt + 1 < 32);
;       s16x8 af[2][4], bf[2][2];
;       auto ldfrag = [&](int ks, int slot) {
; #pragma unroll
;         for (int i = 0; i < 4; ++i) {
;           const int row = wr * 128 + i * 32 + lr;
;           af[slot][i] = *(const s16x8*)(Ab + row * 64 + (((ks * 2 + lh) ^ ((row >> 1) & 7)) * 8));
;         }
; #pragma unroll
;         for (int j = 0; j < 2; ++j) {
;           const int rowb = nh * 128 + wc * 64 + j * 32 + lr;
;           bf[slot][j] = *(const s16x8*)(Bb + rowb * 64 + (((ks * 2 + lh) ^ ((rowb >> 1) & 7)) * 8));
;         }
;       };
;       ldfrag(0, 0);
;       ldfrag(1, 1);
;       __builtin_amdgcn_sched_barrier(0);
; #pragma unroll
;       for (int ks = 0; ks < 4; ++ks) {
;         const int slot = ks & 1;
; #pragma unroll
;         for (int i = 0; i < 4; ++i) {
;           acc[i][0] = mfma32(af[slot][i], bf[slot][0], acc[i][0]);
;           acc[i][1] = mfma32(af[slot][i], bf[slot][1], acc[i][1]);
;           __builtin_amdgcn_sched_barrier(0);
;           if (pre && (i & 1) == 0) {
;             const int pi = ks * 2 + (i >> 1);
;             if (pi < 4) glds16(Ag0 + (size_t)pi * 64 * LDK + (kt + 1) * 64, st + (srow + 64 * pi) * 64 + sch * 8);
;             else glds16(Bg0 + (size_t)(pi - 4) * 64 * LDK + (kt + 1) * 64, st + 16384 + (srow + 64 * (pi - 4)) * 64 + sch * 8);
;             __builtin_amdgcn_sched_barrier(0);
;           }
;         }
;         if (ks + 2 < 4) { ldfrag(ks + 2, slot); __builtin_amdgcn_sched_barrier(0); }
;       }
.Lrot129_loop:
	s_add_i32 s13, s12, 0xffff8000
	s_and_b32 s13, s13, 0x8000
	s_lshl_b32 s13, s13, 1
	v_lshl_or_b32 v128, v143, 1, s13
	v_lshl_add_u32 v149, v147, 1, s13
	s_and_b32 s98, s12, 0x8000
	s_lshl_b32 s98, s98, 1
	s_waitcnt lgkmcnt(7)
	v_mfma_f32_32x32x16_bf16 v[64:79], v[178:181], v[194:197], v[64:79]
	v_add3_u32 v226, s98, v162, v156
	s_waitcnt lgkmcnt(6)
	v_mfma_f32_32x32x16_bf16 v[112:127], v[178:181], v[198:201], v[112:127]
	v_readfirstlane_b32 s100, v226
	s_mov_b32 s20, m0
	s_add_i32 m0, s100, 0x8000
	s_nop 0
	global_load_lds_dwordx4 v[160:161], off
	v_mfma_f32_32x32x16_bf16 v[32:47], v[182:185], v[194:197], v[32:47]
	v_lshl_add_u64 v[178:179], v[160:161], 0, s[2:3]
	s_add_i32 m0, s100, 0xa000
	s_nop 0
	global_load_lds_dwordx4 v[178:179], off
	v_mfma_f32_32x32x16_bf16 v[96:111], v[182:185], v[198:201], v[96:111]
	v_lshl_add_u64 v[180:181], v[160:161], 0, s[4:5]
	s_add_i32 m0, s100, 0xc000
	s_nop 0
	global_load_lds_dwordx4 v[180:181], off
	v_mfma_f32_32x32x16_bf16 v[16:31], v[186:189], v[194:197], v[16:31]
	v_lshl_add_u64 v[178:179], v[160:161], 0, s[6:7]
	s_add_i32 m0, s100, 0xe000
	s_nop 0
	global_load_lds_dwordx4 v[178:179], off
	s_mov_b32 m0, s20
	v_mfma_f32_32x32x16_bf16 v[80:95], v[186:189], v[198:201], v[80:95]
	v_mfma_f32_32x32x16_bf16 v[0:15], v[190:193], v[194:197], v[0:15]
	v_mfma_f32_32x32x16_bf16 v[48:63], v[190:193], v[198:201], v[48:63]
	v_lshl_add_u64 v[160:161], v[160:161], 0, s[8:9]
	v_add_u32_e32 v177, v128, v175
	ds_read_b128 v[178:181], v177
	ds_read_b128 v[182:185], v177 offset:4096
	ds_read_b128 v[186:189], v177 offset:8192
	ds_read_b128 v[190:193], v177 offset:12288
	v_add_u32_e32 v177, v149, v175
	ds_read_b128 v[194:197], v177 offset:32768
	ds_read_b128 v[198:201], v177 offset:36864
	s_waitcnt lgkmcnt(7)
	v_mfma_f32_32x32x16_bf16 v[64:79], v[202:205], v[218:221], v[64:79]
	s_waitcnt lgkmcnt(6)
	v_mfma_f32_32x32x16_bf16 v[112:127], v[202:205], v[222:225], v[112:127]
	v_mfma_f32_32x32x16_bf16 v[32:47], v[206:209], v[218:221], v[32:47]
	v_mfma_f32_32x32x16_bf16 v[96:111], v[206:209], v[222:225], v[96:111]
	v_mfma_f32_32x32x16_bf16 v[16:31], v[210:213], v[218:221], v[16:31]
	v_mfma_f32_32x32x16_bf16 v[80:95], v[210:213], v[222:225], v[80:95]
	v_mfma_f32_32x32x16_bf16 v[0:15], v[214:217], v[218:221], v[0:15]
	v_mfma_f32_32x32x16_bf16 v[48:63], v[214:217], v[222:225], v[48:63]
	v_add_u32_e32 v128, v128, v176
	ds_read_b128 v[202:205], v128
	ds_read_b128 v[206:209], v128 offset:4096
	ds_read_b128 v[210:213], v128 offset:8192
	ds_read_b128 v[214:217], v128 offset:12288
	v_add_u32_e32 v128, v149, v176
	ds_read_b128 v[218:221], v128 offset:32768
	ds_read_b128 v[222:225], v128 offset:36864
	s_waitcnt lgkmcnt(7)
	v_mfma_f32_32x32x16_bf16 v[64:79], v[178:181], v[194:197], v[64:79]
	s_waitcnt lgkmcnt(6)
	v_mfma_f32_32x32x16_bf16 v[112:127], v[178:181], v[198:201], v[112:127]
	v_mfma_f32_32x32x16_bf16 v[32:47], v[182:185], v[194:197], v[32:47]
	v_mfma_f32_32x32x16_bf16 v[96:111], v[182:185], v[198:201], v[96:111]
	v_mfma_f32_32x32x16_bf16 v[16:31], v[186:189], v[194:197], v[16:31]
	v_mfma_f32_32x32x16_bf16 v[80:95], v[186:189], v[198:201], v[80:95]
	v_mfma_f32_32x32x16_bf16 v[0:15], v[190:193], v[194:197], v[0:15]
	v_mfma_f32_32x32x16_bf16 v[48:63], v[190:193], v[198:201], v[48:63]
	v_lshl_or_b32 v227, v143, 1, s98
	v_lshl_add_u32 v229, v147, 1, s98
	v_add_u32_e32 v228, v227, v173
	v_add_u32_e32 v230, v229, v173
	s_waitcnt vmcnt(0) lgkmcnt(0)
	s_barrier
	ds_read_b128 v[178:181], v228
	ds_read_b128 v[182:185], v228 offset:4096
	ds_read_b128 v[186:189], v228 offset:8192
	ds_read_b128 v[190:193], v228 offset:12288
	ds_read_b128 v[194:197], v230 offset:32768
	ds_read_b128 v[198:201], v230 offset:36864
	v_add3_u32 v226, s13, v162, v156
	v_mfma_f32_32x32x16_bf16 v[64:79], v[202:205], v[218:221], v[64:79]
	v_readfirstlane_b32 s99, v226
	s_mov_b32 s20, m0
	s_mov_b32 m0, s99
	s_nop 0
	global_load_lds_dwordx4 v[158:159], off
	v_mfma_f32_32x32x16_bf16 v[112:127], v[202:205], v[222:225], v[112:127]
	v_lshl_add_u64 v[232:233], v[158:159], 0, s[2:3]
	s_add_i32 m0, s99, 0x2000
	s_nop 0
	global_load_lds_dwordx4 v[232:233], off
	v_mfma_f32_32x32x16_bf16 v[32:47], v[206:209], v[218:221], v[32:47]
	v_lshl_add_u64 v[234:235], v[158:159], 0, s[4:5]
	s_add_i32 m0, s99, 0x4000
	s_nop 0
	global_load_lds_dwordx4 v[234:235], off
	v_mfma_f32_32x32x16_bf16 v[96:111], v[206:209], v[222:225], v[96:111]
	v_lshl_add_u64 v[232:233], v[158:159], 0, s[6:7]
	s_add_i32 m0, s99, 0x6000
	s_nop 0
	global_load_lds_dwordx4 v[232:233], off
	s_mov_b32 m0, s20
	v_mfma_f32_32x32x16_bf16 v[16:31], v[210:213], v[218:221], v[16:31]
	v_mfma_f32_32x32x16_bf16 v[80:95], v[210:213], v[222:225], v[80:95]
	v_mfma_f32_32x32x16_bf16 v[0:15], v[214:217], v[218:221], v[0:15]
	v_mfma_f32_32x32x16_bf16 v[48:63], v[214:217], v[222:225], v[48:63]
	v_add_u32_e32 v228, v227, v174
	v_add_u32_e32 v230, v229, v174
	ds_read_b128 v[202:205], v228
	ds_read_b128 v[206:209], v228 offset:4096
	ds_read_b128 v[210:213], v228 offset:8192
	ds_read_b128 v[214:217], v228 offset:12288
	ds_read_b128 v[218:221], v230 offset:32768
	ds_read_b128 v[222:225], v230 offset:36864
	s_add_i32 s12, s12, 0x8000
	v_lshl_add_u64 v[158:159], v[158:159], 0, s[8:9]
	s_cmp_eq_u32 s12, 0xf8000
	s_cbranch_scc0 .Lrot129_loop
; template <int EPI, int PN>
; __device__ void gemm_phase(const Params& p, const u16* __restrict__ A, const u16* __restrict__ Bt, int nNt, char* smem) {
;     ...
;   for (int q = jb;; q += NJ) {
;     const int pl = q / (4 * PN), w = q % (4 * PN);
;     const int gp = pl * 8 + xcd;
;     if (gp >= npatch) break;
;     const int mt = (gp / npn) * 4 + (w & 3), nt = (gp % npn) * PN + (w >> 2);
;     const int gch = sch ^ ((srow >> 1) & 7);
;     const u16* Ag0 = A + (size_t)(mt * 256 + srow) * LDK + gch * 8;
;     const u16* Bg0 = Bt + (size_t)(nt * 256 + srow) * LDK + gch * 8;
;     ...
;     for (int kt = 0; kt < 32; ++kt) {
;       asm volatile("s_waitcnt vmcnt(0)" ::: "memory");
;       __builtin_amdgcn_s_barrier();
;       const u16* Ab = ring + (kt & 1) * STG;
;       const u16* Bb = Ab + 16384;
;       u16* st = ring + ((kt + 1) & 1) * STG;
;       const bool pre = (kt + 1 < 32);
;       s16x8 af[2][4], bf[2][2];
;       auto ldfrag = [&](int ks, int slot) {
; #pragma unroll
;         for (int i = 0; i < 4; ++i) {
;           const int row = wr * 128 + i * 32 + lr;
;           af[slot][i] = *(const s16x8*)(Ab + row * 64 + (((ks * 2 + lh) ^ ((row >> 1) & 7)) * 8));
;         }
; #pragma unroll
;         for (int j = 0; j < 2; ++j) {
;           const int rowb = nh * 128 + wc * 64 + j * 32 + lr;
;           bf[slot][j] = *(const s16x8*)(Bb + rowb * 64 + (((ks * 2 + lh) ^ ((rowb >> 1) & 7)) * 8));
;         }
;       };
;       ldfrag(0, 0);
;       ldfrag(1, 1);
;       __builtin_amdgcn_sched_barrier(0);
; #pragma unroll
;       for (int ks = 0; ks < 4; ++ks) {
;         const int slot = ks & 1;
; #pragma unroll
;         for (int i = 0; i < 4; ++i) {
;           acc[i][0] = mfma32(af[slot][i], bf[slot][0], acc[i][0]);
;           acc[i][1] = mfma32(af[slot][i], bf[slot][1], acc[i][1]);
;           __builtin_amdgcn_sched_barrier(0);
;           if (pre && (i & 1) == 0) {
;             const int pi = ks * 2 + (i >> 1);
;             if (pi < 4) glds16(Ag0 + (size_t)pi * 64 * LDK + (kt + 1) * 64, st + (srow + 64 * pi) * 64 + sch * 8);
;             else glds16(Bg0 + (size_t)(pi - 4) * 64 * LDK + (kt + 1) * 64, st + 16384 + (srow + 64 * (pi - 4)) * 64 + sch * 8);
;             __builtin_amdgcn_sched_barrier(0);
;           }
;         }
;         if (ks + 2 < 4) { ldfrag(ks + 2, slot); __builtin_amdgcn_sched_barrier(0); }
;       }
	s_add_i32 s13, s12, 0xffff8000
	s_and_b32 s13, s13, 0x8000
	s_lshl_b32 s13, s13, 1
	v_lshl_or_b32 v128, v143, 1, s13
	v_lshl_add_u32 v149, v147, 1, s13
	s_and_b32 s98, s12, 0x8000
	s_lshl_b32 s98, s98, 1
	s_waitcnt lgkmcnt(7)
	v_mfma_f32_32x32x16_bf16 v[64:79], v[178:181], v[194:197], v[64:79]
	v_add3_u32 v226, s98, v162, v156
	s_waitcnt lgkmcnt(6)
	v_mfma_f32_32x32x16_bf16 v[112:127], v[178:181], v[198:201], v[112:127]
	v_readfirstlane_b32 s100, v226
	s_mov_b32 s20, m0
	s_add_i32 m0, s100, 0x8000
	s_nop 0
	global_load_lds_dwordx4 v[160:161], off
	v_mfma_f32_32x32x16_bf16 v[32:47], v[182:185], v[194:197], v[32:47]
	v_lshl_add_u64 v[178:179], v[160:161], 0, s[2:3]
	s_add_i32 m0, s100, 0xa000
	s_nop 0
	global_load_lds_dwordx4 v[178:179], off
	v_mfma_f32_32x32x16_bf16 v[96:111], v[182:185], v[198:201], v[96:111]
	v_lshl_add_u64 v[180:181], v[160:161], 0, s[4:5]
	s_add_i32 m0, s100, 0xc000
	s_nop 0
	global_load_lds_dwordx4 v[180:181], off
	v_mfma_f32_32x32x16_bf16 v[16:31], v[186:189], v[194:197], v[16:31]
	v_lshl_add_u64 v[178:179], v[160:161], 0, s[6:7]
	s_add_i32 m0, s100, 0xe000
	s_nop 0
	global_load_lds_dwordx4 v[178:179], off
	s_mov_b32 m0, s20
	v_mfma_f32_32x32x16_bf16 v[80:95], v[186:189], v[198:201], v[80:95]
	v_mfma_f32_32x32x16_bf16 v[0:15], v[190:193], v[194:197], v[0:15]
	v_mfma_f32_32x32x16_bf16 v[48:63], v[190:193], v[198:201], v[48:63]
	v_lshl_add_u64 v[160:161], v[160:161], 0, s[8:9]
	v_add_u32_e32 v177, v128, v175
	ds_read_b128 v[178:181], v177
	ds_read_b128 v[182:185], v177 offset:4096
	ds_read_b128 v[186:189], v177 offset:8192
	ds_read_b128 v[190:193], v177 offset:12288
	v_add_u32_e32 v177, v149, v175
	ds_read_b128 v[194:197], v177 offset:32768
	ds_read_b128 v[198:201], v177 offset:36864
	s_waitcnt lgkmcnt(7)
	v_mfma_f32_32x32x16_bf16 v[64:79], v[202:205], v[218:221], v[64:79]
	s_waitcnt lgkmcnt(6)
	v_mfma_f32_32x32x16_bf16 v[112:127], v[202:205], v[222:225], v[112:127]
	v_mfma_f32_32x32x16_bf16 v[32:47], v[206:209], v[218:221], v[32:47]
	v_mfma_f32_32x32x16_bf16 v[96:111], v[206:209], v[222:225], v[96:111]
	v_mfma_f32_32x32x16_bf16 v[16:31], v[210:213], v[218:221], v[16:31]
	v_mfma_f32_32x32x16_bf16 v[80:95], v[210:213], v[222:225], v[80:95]
	v_mfma_f32_32x32x16_bf16 v[0:15], v[214:217], v[218:221], v[0:15]
	v_mfma_f32_32x32x16_bf16 v[48:63], v[214:217], v[222:225], v[48:63]
	v_add_u32_e32 v128, v128, v176
	ds_read_b128 v[202:205], v128
	ds_read_b128 v[206:209], v128 offset:4096
	ds_read_b128 v[210:213], v128 offset:8192
	ds_read_b128 v[214:217], v128 offset:12288
	v_add_u32_e32 v128, v149, v176
	ds_read_b128 v[218:221], v128 offset:32768
	ds_read_b128 v[222:225], v128 offset:36864
	v_readlane_b32 s98, v254, 28
	v_readlane_b32 s99, v254, 24
	s_nop 1
	s_add_i32 s98, s19, s98
	s_mul_hi_i32 s100, s98, 0xb21642c9
	s_add_i32 s100, s100, s98
	s_lshr_b32 s101, s100, 31
	s_ashr_i32 s100, s100, 6
	s_add_i32 s100, s100, s101
	s_lshl_b32 s101, s100, 3
	s_or_b32 s101, s101, s99
	s_cmp_lt_i32 s101, 32
	s_cselect_b32 s98, s98, s19
	s_mul_hi_i32 s100, s98, 0xb21642c9
	s_add_i32 s100, s100, s98
	s_lshr_b32 s101, s100, 31
	s_ashr_i32 s100, s100, 6
	s_add_i32 s100, s100, s101
	s_mul_i32 s101, s100, 0x5c
	s_sub_i32 s101, s98, s101
	s_lshl_b32 s100, s100, 3
	s_or_b32 s100, s100, s99
	s_and_b32 s99, s101, 3
	s_lshl_b32 s100, s100, 2
	s_or_b32 s100, s100, s99
	s_ashr_i32 s101, s101, 2
	v_lshrrev_b32_e32 v236, 6, v252
	v_and_b32_e32 v237, 3, v236
	v_lshl_add_u32 v237, v237, 6, v135
	v_mov_b32_e32 v238, s101
	v_mov_b32_e32 v239, s100
	v_cmp_gt_u32_e32 vcc, 4, v236
	v_readlane_b32 s98, v253, 29
	v_readlane_b32 s99, v253, 30
	v_readlane_b32 s100, v253, 31
	v_readlane_b32 s101, v253, 32
	v_cndmask_b32_e32 v238, v238, v239, vcc
	v_lshl_add_u32 v237, v238, 8, v237
	v_mov_b32_e32 v240, s100
	v_mov_b32_e32 v241, s101
	v_mov_b32_e32 v242, s98
	v_mov_b32_e32 v243, s99
	v_cndmask_b32_e32 v240, v240, v242, vcc
	v_cndmask_b32_e32 v241, v241, v243, vcc
	v_mad_u64_u32 v[240:241], s[98:99], v237, s0, v[240:241]
	global_load_dword v236, v[240:241], off
	global_load_dword v237, v[240:241], off offset:128
	s_waitcnt lgkmcnt(7)
	v_mfma_f32_32x32x16_bf16 v[64:79], v[178:181], v[194:197], v[64:79]
	s_waitcnt lgkmcnt(6)
	v_mfma_f32_32x32x16_bf16 v[112:127], v[178:181], v[198:201], v[112:127]
	v_mfma_f32_32x32x16_bf16 v[32:47], v[182:185], v[194:197], v[32:47]
	v_mfma_f32_32x32x16_bf16 v[96:111], v[182:185], v[198:201], v[96:111]
	v_mfma_f32_32x32x16_bf16 v[16:31], v[186:189], v[194:197], v[16:31]
	v_mfma_f32_32x32x16_bf16 v[80:95], v[186:189], v[198:201], v[80:95]
	v_mfma_f32_32x32x16_bf16 v[0:15], v[190:193], v[194:197], v[0:15]
	v_mfma_f32_32x32x16_bf16 v[48:63], v[190:193], v[198:201], v[48:63]
	s_waitcnt lgkmcnt(1)
	v_mfma_f32_32x32x16_bf16 v[64:79], v[202:205], v[218:221], v[64:79]
	s_waitcnt lgkmcnt(0)
	v_mfma_f32_32x32x16_bf16 v[112:127], v[202:205], v[222:225], v[112:127]
	v_mfma_f32_32x32x16_bf16 v[32:47], v[206:209], v[218:221], v[32:47]
	v_mfma_f32_32x32x16_bf16 v[96:111], v[206:209], v[222:225], v[96:111]
	v_mfma_f32_32x32x16_bf16 v[16:31], v[210:213], v[218:221], v[16:31]
	v_mfma_f32_32x32x16_bf16 v[80:95], v[210:213], v[222:225], v[80:95]
	v_mfma_f32_32x32x16_bf16 v[0:15], v[214:217], v[218:221], v[0:15]
	v_mfma_f32_32x32x16_bf16 v[48:63], v[214:217], v[222:225], v[48:63]
	s_waitcnt vmcnt(2)
	s_barrier
; __device__ __forceinline__ int accrow(int reg, int lh) { return (reg & 3) + 8 * (reg >> 2) + 4 * lh; }
; template <int EPI, int PN>
; __device__ void gemm_phase(const Params& p, const u16* __restrict__ A, const u16* __restrict__ Bt, int nNt, char* smem) {
;     ...
;       for (int ks = 0; ks < 4; ++ks) {
;         const int slot = ks & 1;
; #pragma unroll
;         for (int i = 0; i < 4; ++i) {
;           acc[i][0] = mfma32(af[slot][i], bf[slot][0], acc[i][0]);
;           acc[i][1] = mfma32(af[slot][i], bf[slot][1], acc[i][1]);
;           __builtin_amdgcn_sched_barrier(0);
;           if (pre && (i & 1) == 0) {
;             const int pi = ks * 2 + (i >> 1);
;             if (pi < 4) glds16(Ag0 + (size_t)pi * 64 * LDK + (kt + 1) * 64, st + (srow + 64 * pi) * 64 + sch * 8);
;             else glds16(Bg0 + (size_t)(pi - 4) * 64 * LDK + (kt + 1) * 64, st + 16384 + (srow + 64 * (pi - 4)) * 64 + sch * 8);
;             __builtin_amdgcn_sched_barrier(0);
;           }
;         }
;         if (ks + 2 < 4) { ldfrag(ks + 2, slot); __builtin_amdgcn_sched_barrier(0); }
;       }
;     ...
;     } else if (EPI == 0 && col0 >= NPROJ) {
; #pragma unroll
;       for (int i = 0; i < 4; ++i)
; #pragma unroll
;         for (int r = 0; r < 16; ++r) {
;           const size_t row = row0 + i * 32 + accrow(r, lhE);
;           const int col = col0 + lrE;
;           if (col < NIN) p.dtraw[row * 16 + (col - NPROJ)] = acc[i][0][r];
;         }
;     } else {
; #pragma unroll
;       for (int i = 0; i < 4; ++i)
; #pragma unroll
;         for (int j = 0; j < 2; ++j)
; #pragma unroll
;           for (int r = 0; r < 16; ++r) *(u16*)(et + (i * 32 + accrow(r, lhE)) * 144 + (j * 32 + lrE) * 2) = f2bf(acc[i][j][r]);
	ds_read_b128 v[158:161], v164
	ds_read_b128 v[178:181], v164 offset:4096
	ds_read_b128 v[182:185], v164 offset:8192
	ds_read_b128 v[186:189], v164 offset:12288
	ds_read_b128 v[190:193], v165
	ds_read_b128 v[194:197], v165 offset:4096
	ds_read_b128 v[198:201], v166
	ds_read_b128 v[202:205], v166 offset:4096
	ds_read_b128 v[206:209], v166 offset:8192
	ds_read_b128 v[210:213], v166 offset:12288
	ds_read_b128 v[214:217], v168
	ds_read_b128 v[218:221], v168 offset:4096
	s_waitcnt lgkmcnt(7)
	v_mfma_f32_32x32x16_bf16 v[64:79], v[158:161], v[190:193], v[64:79]
	s_waitcnt lgkmcnt(6)
	v_mfma_f32_32x32x16_bf16 v[112:127], v[158:161], v[194:197], v[112:127]
	v_mfma_f32_32x32x16_bf16 v[32:47], v[178:181], v[190:193], v[32:47]
	v_mfma_f32_32x32x16_bf16 v[96:111], v[178:181], v[194:197], v[96:111]
	v_mfma_f32_32x32x16_bf16 v[16:31], v[182:185], v[190:193], v[16:31]
	v_mfma_f32_32x32x16_bf16 v[80:95], v[182:185], v[194:197], v[80:95]
	v_mfma_f32_32x32x16_bf16 v[0:15], v[186:189], v[190:193], v[0:15]
	v_mfma_f32_32x32x16_bf16 v[48:63], v[186:189], v[194:197], v[48:63]
	ds_read_b128 v[158:161], v169
	ds_read_b128 v[178:181], v169 offset:4096
	ds_read_b128 v[182:185], v169 offset:8192
	ds_read_b128 v[186:189], v169 offset:12288
	ds_read_b128 v[190:193], v170
	ds_read_b128 v[194:197], v170 offset:4096
	s_waitcnt lgkmcnt(7)
	v_mfma_f32_32x32x16_bf16 v[64:79], v[198:201], v[214:217], v[64:79]
	s_waitcnt lgkmcnt(6)
	v_mfma_f32_32x32x16_bf16 v[112:127], v[198:201], v[218:221], v[112:127]
	v_mfma_f32_32x32x16_bf16 v[32:47], v[202:205], v[214:217], v[32:47]
	v_mfma_f32_32x32x16_bf16 v[96:111], v[202:205], v[218:221], v[96:111]
	v_mfma_f32_32x32x16_bf16 v[16:31], v[206:209], v[214:217], v[16:31]
	v_mfma_f32_32x32x16_bf16 v[80:95], v[206:209], v[218:221], v[80:95]
	v_mfma_f32_32x32x16_bf16 v[0:15], v[210:213], v[214:217], v[0:15]
	v_mfma_f32_32x32x16_bf16 v[48:63], v[210:213], v[218:221], v[48:63]
	ds_read_b128 v[198:201], v171
	ds_read_b128 v[202:205], v171 offset:4096
	ds_read_b128 v[206:209], v171 offset:8192
	ds_read_b128 v[210:213], v171 offset:12288
	ds_read_b128 v[214:217], v172
	ds_read_b128 v[218:221], v172 offset:4096
	s_waitcnt lgkmcnt(7)
	v_mfma_f32_32x32x16_bf16 v[64:79], v[158:161], v[190:193], v[64:79]
	s_waitcnt lgkmcnt(6)
	v_mfma_f32_32x32x16_bf16 v[112:127], v[158:161], v[194:197], v[112:127]
	v_mfma_f32_32x32x16_bf16 v[32:47], v[178:181], v[190:193], v[32:47]
	v_mfma_f32_32x32x16_bf16 v[96:111], v[178:181], v[194:197], v[96:111]
	v_mfma_f32_32x32x16_bf16 v[16:31], v[182:185], v[190:193], v[16:31]
	v_mfma_f32_32x32x16_bf16 v[80:95], v[182:185], v[194:197], v[80:95]
	v_mfma_f32_32x32x16_bf16 v[0:15], v[186:189], v[190:193], v[0:15]
	v_mfma_f32_32x32x16_bf16 v[48:63], v[186:189], v[194:197], v[48:63]
	s_waitcnt lgkmcnt(1)
	v_mfma_f32_32x32x16_bf16 v[64:79], v[198:201], v[214:217], v[64:79]
	s_waitcnt lgkmcnt(0)
	v_mfma_f32_32x32x16_bf16 v[112:127], v[198:201], v[218:221], v[112:127]
	v_mfma_f32_32x32x16_bf16 v[32:47], v[202:205], v[214:217], v[32:47]
	v_mfma_f32_32x32x16_bf16 v[96:111], v[202:205], v[218:221], v[96:111]
	v_mfma_f32_32x32x16_bf16 v[16:31], v[206:209], v[214:217], v[16:31]
	v_mfma_f32_32x32x16_bf16 v[80:95], v[206:209], v[218:221], v[80:95]
	v_mfma_f32_32x32x16_bf16 v[0:15], v[210:213], v[214:217], v[0:15]
	v_mfma_f32_32x32x16_bf16 v[48:63], v[210:213], v[218:221], v[48:63]
	v_mov_b32_e32 v128, v139
	v_mov_b32_e32 v161, v137
	v_mov_b32_e32 v177, v135
	s_barrier
	s_nop 0
	v_lshl_add_u32 v160, s11, 8, v145
	s_ashr_i32 s11, s10, 31
	s_lshl_b64 s[10:11], s[10:11], 8
	v_mov_b32_e32 v159, s11
	v_or_b32_e32 v158, s10, v134
	v_cmp_gt_i32_e32 vcc, s14, v160
	s_and_saveexec_b64 s[10:11], vcc
	s_xor_b64 s[10:11], exec, s[10:11]
	s_cbranch_execz .LBB0_132
	v_lshlrev_b32_e32 v149, 1, v161
	v_mul_lo_u32 v128, v128, s15
	v_add3_u32 v128, v163, v149, v128
	v_cvt_pk_bf16_f32 v0, v0, s0
	v_cvt_pk_bf16_f32 v64, v64, s0
	v_cvt_pk_bf16_f32 v32, v32, s0
	v_cvt_pk_bf16_f32 v16, v16, s0
	ds_write_b16 v128, v0 offset:13824
	v_cvt_pk_bf16_f32 v0, v1, s0
	ds_write_b16 v128, v64
	v_cvt_pk_bf16_f32 v64, v65, s0
	ds_write_b16 v128, v32 offset:4608
	v_cvt_pk_bf16_f32 v32, v33, s0
	ds_write_b16 v128, v16 offset:9216
	v_cvt_pk_bf16_f32 v16, v17, s0
	ds_write_b16 v128, v0 offset:13968
	v_cvt_pk_bf16_f32 v0, v2, s0
	ds_write_b16 v128, v64 offset:144
	v_cvt_pk_bf16_f32 v64, v66, s0
	ds_write_b16 v128, v32 offset:4752
	v_cvt_pk_bf16_f32 v32, v34, s0
	ds_write_b16 v128, v16 offset:9360
	v_cvt_pk_bf16_f32 v16, v18, s0
	ds_write_b16 v128, v0 offset:14112
	v_cvt_pk_bf16_f32 v0, v3, s0
	ds_write_b16 v128, v64 offset:288
	v_cvt_pk_bf16_f32 v64, v67, s0
	ds_write_b16 v128, v32 offset:4896
	v_cvt_pk_bf16_f32 v32, v35, s0
	ds_write_b16 v128, v16 offset:9504
	v_cvt_pk_bf16_f32 v16, v19, s0
	ds_write_b16 v128, v0 offset:14256
	v_cvt_pk_bf16_f32 v0, v4, s0
	ds_write_b16 v128, v64 offset:432
	v_cvt_pk_bf16_f32 v64, v68, s0
	ds_write_b16 v128, v32 offset:5040
	v_cvt_pk_bf16_f32 v32, v36, s0
	ds_write_b16 v128, v16 offset:9648
	v_cvt_pk_bf16_f32 v16, v20, s0
	ds_write_b16 v128, v0 offset:14976
	v_cvt_pk_bf16_f32 v0, v5, s0
	ds_write_b16 v128, v64 offset:1152
	v_cvt_pk_bf16_f32 v64, v69, s0
	ds_write_b16 v128, v32 offset:5760
	v_cvt_pk_bf16_f32 v32, v37, s0
	ds_write_b16 v128, v16 offset:10368
	v_cvt_pk_bf16_f32 v16, v21, s0
	ds_write_b16 v128, v0 offset:15120
	v_cvt_pk_bf16_f32 v0, v6, s0
	ds_write_b16 v128, v64 offset:1296
	v_cvt_pk_bf16_f32 v64, v70, s0
	ds_write_b16 v128, v32 offset:5904
	v_cvt_pk_bf16_f32 v32, v38, s0
	ds_write_b16 v128, v16 offset:10512
	v_cvt_pk_bf16_f32 v16, v22, s0
	ds_write_b16 v128, v0 offset:15264
	v_cvt_pk_bf16_f32 v0, v7, s0
	ds_write_b16 v128, v64 offset:1440
; __device__ __forceinline__ int accrow(int reg, int lh) { return (reg & 3) + 8 * (reg >> 2) + 4 * lh; }
; template <int EPI, int PN>
; __device__ void gemm_phase(const Params& p, const u16* __restrict__ A, const u16* __restrict__ Bt, int nNt, char* smem) {
;     ...
; #pragma unroll
;       for (int i = 0; i < 4; ++i)
; #pragma unroll
;         for (int j = 0; j < 2; ++j)
; #pragma unroll
;           for (int r = 0; r < 16; ++r) *(u16*)(et + (i * 32 + accrow(r, lhE)) * 144 + (j * 32 + lrE) * 2) = f2bf(acc[i][j][r]);
	v_cvt_pk_bf16_f32 v64, v71, s0
	ds_write_b16 v128, v32 offset:6048
	v_cvt_pk_bf16_f32 v32, v39, s0
	ds_write_b16 v128, v16 offset:10656
	v_cvt_pk_bf16_f32 v16, v23, s0
	ds_write_b16 v128, v0 offset:15408
	v_cvt_pk_bf16_f32 v0, v8, s0
	ds_write_b16 v128, v64 offset:1584
	v_cvt_pk_bf16_f32 v64, v72, s0
	ds_write_b16 v128, v32 offset:6192
	v_cvt_pk_bf16_f32 v32, v40, s0
	ds_write_b16 v128, v16 offset:10800
	v_cvt_pk_bf16_f32 v16, v24, s0
	ds_write_b16 v128, v0 offset:16128
	v_cvt_pk_bf16_f32 v0, v9, s0
	ds_write_b16 v128, v64 offset:2304
	v_cvt_pk_bf16_f32 v64, v73, s0
	ds_write_b16 v128, v32 offset:6912
	v_cvt_pk_bf16_f32 v32, v41, s0
	ds_write_b16 v128, v16 offset:11520
	v_cvt_pk_bf16_f32 v16, v25, s0
	ds_write_b16 v128, v0 offset:16272
	v_cvt_pk_bf16_f32 v0, v10, s0
	ds_write_b16 v128, v64 offset:2448
	v_cvt_pk_bf16_f32 v64, v74, s0
	ds_write_b16 v128, v32 offset:7056
	v_cvt_pk_bf16_f32 v32, v42, s0
	ds_write_b16 v128, v16 offset:11664
	v_cvt_pk_bf16_f32 v16, v26, s0
	ds_write_b16 v128, v0 offset:16416
	v_cvt_pk_bf16_f32 v0, v11, s0
	ds_write_b16 v128, v64 offset:2592
	v_cvt_pk_bf16_f32 v64, v75, s0
	ds_write_b16 v128, v32 offset:7200
	v_cvt_pk_bf16_f32 v32, v43, s0
	ds_write_b16 v128, v16 offset:11808
	v_cvt_pk_bf16_f32 v16, v27, s0
	ds_write_b16 v128, v0 offset:16560
	v_cvt_pk_bf16_f32 v0, v12, s0
	ds_write_b16 v128, v64 offset:2736
	v_cvt_pk_bf16_f32 v64, v76, s0
	ds_write_b16 v128, v32 offset:7344
	v_cvt_pk_bf16_f32 v32, v44, s0
	ds_write_b16 v128, v16 offset:11952
	v_cvt_pk_bf16_f32 v16, v28, s0
	ds_write_b16 v128, v0 offset:17280
	v_cvt_pk_bf16_f32 v0, v13, s0
	ds_write_b16 v128, v64 offset:3456
	v_cvt_pk_bf16_f32 v64, v77, s0
	ds_write_b16 v128, v32 offset:8064
	v_cvt_pk_bf16_f32 v32, v45, s0
	ds_write_b16 v128, v16 offset:12672
	v_cvt_pk_bf16_f32 v16, v29, s0
	ds_write_b16 v128, v0 offset:17424
	v_cvt_pk_bf16_f32 v0, v14, s0
	ds_write_b16 v128, v64 offset:3600
	v_cvt_pk_bf16_f32 v64, v78, s0
	ds_write_b16 v128, v32 offset:8208
	v_cvt_pk_bf16_f32 v32, v46, s0
	ds_write_b16 v128, v16 offset:12816
	v_cvt_pk_bf16_f32 v16, v30, s0
	ds_write_b16 v128, v0 offset:17568
	v_cvt_pk_bf16_f32 v0, v15, s0
	ds_write_b16 v128, v64 offset:3744
	v_cvt_pk_bf16_f32 v64, v79, s0
	ds_write_b16 v128, v32 offset:8352
	v_cvt_pk_bf16_f32 v32, v47, s0
	ds_write_b16 v128, v16 offset:12960
	v_cvt_pk_bf16_f32 v16, v31, s0
	ds_write_b16 v128, v0 offset:17712
	v_cvt_pk_bf16_f32 v0, v48, s0
	ds_write_b16 v128, v64 offset:3888
	v_cvt_pk_bf16_f32 v64, v112, s0
	ds_write_b16 v128, v32 offset:8496
	v_cvt_pk_bf16_f32 v32, v96, s0
	ds_write_b16 v128, v16 offset:13104
	v_cvt_pk_bf16_f32 v16, v80, s0
	ds_write_b16 v128, v0 offset:13888
	v_cvt_pk_bf16_f32 v0, v49, s0
	ds_write_b16 v128, v64 offset:64
	v_cvt_pk_bf16_f32 v64, v113, s0
	ds_write_b16 v128, v32 offset:4672
	v_cvt_pk_bf16_f32 v32, v97, s0
	ds_write_b16 v128, v16 offset:9280
	v_cvt_pk_bf16_f32 v16, v81, s0
	ds_write_b16 v128, v0 offset:14032
	v_cvt_pk_bf16_f32 v0, v50, s0
	ds_write_b16 v128, v64 offset:208
	v_cvt_pk_bf16_f32 v64, v114, s0
	ds_write_b16 v128, v32 offset:4816
	v_cvt_pk_bf16_f32 v32, v98, s0
	ds_write_b16 v128, v16 offset:9424
	v_cvt_pk_bf16_f32 v16, v82, s0
	ds_write_b16 v128, v0 offset:14176
	v_cvt_pk_bf16_f32 v0, v51, s0
	ds_write_b16 v128, v64 offset:352
	v_cvt_pk_bf16_f32 v64, v115, s0
	ds_write_b16 v128, v32 offset:4960
	v_cvt_pk_bf16_f32 v32, v99, s0
	ds_write_b16 v128, v16 offset:9568
	v_cvt_pk_bf16_f32 v16, v83, s0
	ds_write_b16 v128, v0 offset:14320
	v_cvt_pk_bf16_f32 v0, v52, s0
	ds_write_b16 v128, v64 offset:496
	v_cvt_pk_bf16_f32 v64, v116, s0
	ds_write_b16 v128, v32 offset:5104
	v_cvt_pk_bf16_f32 v32, v100, s0
	ds_write_b16 v128, v16 offset:9712
	v_cvt_pk_bf16_f32 v16, v84, s0
	ds_write_b16 v128, v0 offset:15040
	v_cvt_pk_bf16_f32 v0, v53, s0
	ds_write_b16 v128, v64 offset:1216
	v_cvt_pk_bf16_f32 v64, v117, s0
	ds_write_b16 v128, v32 offset:5824
	v_cvt_pk_bf16_f32 v32, v101, s0
	ds_write_b16 v128, v16 offset:10432
	v_cvt_pk_bf16_f32 v16, v85, s0
	ds_write_b16 v128, v0 offset:15184
	v_cvt_pk_bf16_f32 v0, v54, s0
	ds_write_b16 v128, v64 offset:1360
	v_cvt_pk_bf16_f32 v64, v118, s0
	ds_write_b16 v128, v32 offset:5968
	v_cvt_pk_bf16_f32 v32, v102, s0
	ds_write_b16 v128, v16 offset:10576
	v_cvt_pk_bf16_f32 v16, v86, s0
	ds_write_b16 v128, v0 offset:15328
	v_cvt_pk_bf16_f32 v0, v55, s0
	ds_write_b16 v128, v64 offset:1504
	v_cvt_pk_bf16_f32 v64, v119, s0
	ds_write_b16 v128, v32 offset:6112
	v_cvt_pk_bf16_f32 v32, v103, s0
	ds_write_b16 v128, v16 offset:10720
	v_cvt_pk_bf16_f32 v16, v87, s0
	ds_write_b16 v128, v0 offset:15472
	v_cvt_pk_bf16_f32 v0, v56, s0
	ds_write_b16 v128, v64 offset:1648
	v_cvt_pk_bf16_f32 v64, v120, s0
	ds_write_b16 v128, v32 offset:6256
	v_cvt_pk_bf16_f32 v32, v104, s0
	ds_write_b16 v128, v16 offset:10864
	v_cvt_pk_bf16_f32 v16, v88, s0
	ds_write_b16 v128, v0 offset:16192
	v_cvt_pk_bf16_f32 v0, v57, s0
	ds_write_b16 v128, v64 offset:2368
	v_cvt_pk_bf16_f32 v64, v121, s0
	ds_write_b16 v128, v32 offset:6976
	v_cvt_pk_bf16_f32 v32, v105, s0
	ds_write_b16 v128, v16 offset:11584
	v_cvt_pk_bf16_f32 v16, v89, s0
	ds_write_b16 v128, v0 offset:16336
	v_cvt_pk_bf16_f32 v0, v58, s0
	ds_write_b16 v128, v64 offset:2512
	v_cvt_pk_bf16_f32 v64, v122, s0
	ds_write_b16 v128, v32 offset:7120
	v_cvt_pk_bf16_f32 v32, v106, s0
	ds_write_b16 v128, v16 offset:11728
	v_cvt_pk_bf16_f32 v16, v90, s0
	ds_write_b16 v128, v0 offset:16480
	v_cvt_pk_bf16_f32 v0, v59, s0
	ds_write_b16 v128, v64 offset:2656
	v_cvt_pk_bf16_f32 v64, v123, s0
	ds_write_b16 v128, v32 offset:7264
	v_cvt_pk_bf16_f32 v32, v107, s0
	ds_write_b16 v128, v16 offset:11872
	v_cvt_pk_bf16_f32 v16, v91, s0
	ds_write_b16 v128, v0 offset:16624
; __device__ __forceinline__ int accrow(int reg, int lh) { return (reg & 3) + 8 * (reg >> 2) + 4 * lh; }
; template <int EPI, int PN>
; __device__ void gemm_phase(const Params& p, const u16* __restrict__ A, const u16* __restrict__ Bt, int nNt, char* smem) {
;     ...
; #pragma unroll
;       for (int i = 0; i < 4; ++i)
; #pragma unroll
;         for (int j = 0; j < 2; ++j)
; #pragma unroll
;           for (int r = 0; r < 16; ++r) *(u16*)(et + (i * 32 + accrow(r, lhE)) * 144 + (j * 32 + lrE) * 2) = f2bf(acc[i][j][r]);
; #pragma unroll
;       for (int it = 0; it < 16; ++it) {
;         const int c = it * 64 + laneE, row = c >> 3, seg = c & 7;
;         const uint4 v = *(const uint4*)(et + row * 144 + seg * 16);
;         if (EPI == 0) *(uint4*)(p.proj + (row0 + row) * NPROJ + col0 + seg * 8) = v;
;         else *(uint4*)(p.qp + (row0 + row) * DM + col0 + seg * 8) = v;
;       }
	v_cvt_pk_bf16_f32 v0, v60, s0
	ds_write_b16 v128, v64 offset:2800
	v_cvt_pk_bf16_f32 v64, v124, s0
	ds_write_b16 v128, v32 offset:7408
	v_cvt_pk_bf16_f32 v32, v108, s0
	ds_write_b16 v128, v16 offset:12016
	v_cvt_pk_bf16_f32 v16, v92, s0
	ds_write_b16 v128, v0 offset:17344
	v_cvt_pk_bf16_f32 v0, v61, s0
	ds_write_b16 v128, v64 offset:3520
	v_cvt_pk_bf16_f32 v64, v125, s0
	ds_write_b16 v128, v32 offset:8128
	v_cvt_pk_bf16_f32 v32, v109, s0
	ds_write_b16 v128, v16 offset:12736
	v_cvt_pk_bf16_f32 v16, v93, s0
	ds_write_b16 v128, v0 offset:17488
	v_cvt_pk_bf16_f32 v0, v62, s0
	ds_write_b16 v128, v64 offset:3664
	v_cvt_pk_bf16_f32 v64, v126, s0
	ds_write_b16 v128, v32 offset:8272
	v_cvt_pk_bf16_f32 v32, v110, s0
	ds_write_b16 v128, v16 offset:12880
	v_cvt_pk_bf16_f32 v16, v94, s0
	ds_write_b16 v128, v0 offset:17632
	v_cvt_pk_bf16_f32 v0, v63, s0
	ds_write_b16 v128, v64 offset:3808
	v_cvt_pk_bf16_f32 v64, v127, s0
	ds_write_b16 v128, v32 offset:8416
	v_cvt_pk_bf16_f32 v32, v111, s0
	ds_write_b16 v128, v16 offset:13024
	v_cvt_pk_bf16_f32 v16, v95, s0
	ds_write_b16 v128, v0 offset:17776
	v_lshlrev_b32_e32 v0, 4, v177
	ds_write_b16 v128, v64 offset:3952
	ds_write_b16 v128, v32 offset:8560
	ds_write_b16 v128, v16 offset:13168
	v_and_b32_e32 v128, 0x70, v0
	v_add_u32_e32 v0, v163, v128
	v_ashrrev_i32_e32 v6, 3, v177
	v_readlane_b32 s36, v253, 39
	v_mad_u64_u32 v[2:3], s[12:13], v6, s16, v[0:1]
	v_ashrrev_i32_e32 v7, 31, v6
	v_readlane_b32 s40, v253, 43
	v_readlane_b32 s41, v253, 44
	ds_read_b128 v[2:5], v2
	v_lshl_add_u64 v[6:7], v[158:159], 0, v[6:7]
	v_mov_b64_e32 v[10:11], s[40:41]
	v_ashrrev_i32_e32 v161, 31, v160
	v_mad_u64_u32 v[8:9], s[12:13], v6, s17, v[10:11]
	v_mad_i32_i24 v9, v7, s17, v9
	v_lshlrev_b64 v[12:13], 1, v[160:161]
	v_add_u32_e32 v1, 64, v177
	v_lshl_add_u64 v[6:7], v[8:9], 0, v[12:13]
	v_ashrrev_i32_e32 v16, 3, v1
	v_lshl_add_u64 v[14:15], v[6:7], 0, v[128:129]
	v_mad_u64_u32 v[6:7], s[12:13], v16, s16, v[0:1]
	v_ashrrev_i32_e32 v17, 31, v16
	ds_read_b128 v[6:9], v6
	s_waitcnt lgkmcnt(1)
	global_store_dwordx4 v[14:15], v[2:5], off sc1
	v_add_u32_e32 v1, 0x80, v177
	v_readlane_b32 s37, v253, 40
	v_lshl_add_u64 v[2:3], v[158:159], 0, v[16:17]
	v_mad_u64_u32 v[4:5], s[12:13], v2, s17, v[10:11]
	v_mad_i32_i24 v5, v3, s17, v5
	v_lshl_add_u64 v[2:3], v[4:5], 0, v[12:13]
	v_lshl_add_u64 v[2:3], v[2:3], 0, v[128:129]
	s_waitcnt lgkmcnt(0)
	global_store_dwordx4 v[2:3], v[6:9], off sc1
	v_readlane_b32 s38, v253, 41
	v_readlane_b32 s39, v253, 42
	v_ashrrev_i32_e32 v6, 3, v1
	v_mad_u64_u32 v[2:3], s[12:13], v6, s16, v[0:1]
	v_ashrrev_i32_e32 v7, 31, v6
	ds_read_b128 v[2:5], v2
	v_lshl_add_u64 v[6:7], v[158:159], 0, v[6:7]
	v_mad_u64_u32 v[8:9], s[12:13], v6, s17, v[10:11]
	v_mad_i32_i24 v9, v7, s17, v9
	v_add_u32_e32 v1, 0xc0, v177
	v_lshl_add_u64 v[6:7], v[8:9], 0, v[12:13]
	v_ashrrev_i32_e32 v16, 3, v1
	v_lshl_add_u64 v[14:15], v[6:7], 0, v[128:129]
	v_mad_u64_u32 v[6:7], s[12:13], v16, s16, v[0:1]
	v_ashrrev_i32_e32 v17, 31, v16
	ds_read_b128 v[6:9], v6
	s_waitcnt lgkmcnt(1)
	global_store_dwordx4 v[14:15], v[2:5], off sc1
	v_add_u32_e32 v1, 0x100, v177
	v_readlane_b32 s42, v253, 45
	v_lshl_add_u64 v[2:3], v[158:159], 0, v[16:17]
	v_mad_u64_u32 v[4:5], s[12:13], v2, s17, v[10:11]
	v_mad_i32_i24 v5, v3, s17, v5
	v_lshl_add_u64 v[2:3], v[4:5], 0, v[12:13]
	v_lshl_add_u64 v[2:3], v[2:3], 0, v[128:129]
	s_waitcnt lgkmcnt(0)
	global_store_dwordx4 v[2:3], v[6:9], off sc1
	v_readlane_b32 s43, v253, 46
	v_readlane_b32 s44, v253, 47
	v_ashrrev_i32_e32 v6, 3, v1
	v_mad_u64_u32 v[2:3], s[12:13], v6, s16, v[0:1]
	v_ashrrev_i32_e32 v7, 31, v6
	ds_read_b128 v[2:5], v2
	v_lshl_add_u64 v[6:7], v[158:159], 0, v[6:7]
	v_mad_u64_u32 v[8:9], s[12:13], v6, s17, v[10:11]
	v_mad_i32_i24 v9, v7, s17, v9
	v_add_u32_e32 v1, 0x140, v177
	v_lshl_add_u64 v[6:7], v[8:9], 0, v[12:13]
	v_ashrrev_i32_e32 v16, 3, v1
	v_lshl_add_u64 v[14:15], v[6:7], 0, v[128:129]
	v_mad_u64_u32 v[6:7], s[12:13], v16, s16, v[0:1]
	v_ashrrev_i32_e32 v17, 31, v16
	ds_read_b128 v[6:9], v6
	s_waitcnt lgkmcnt(1)
	global_store_dwordx4 v[14:15], v[2:5], off sc1
	v_add_u32_e32 v1, 0x180, v177
	v_readlane_b32 s45, v253, 48
	v_lshl_add_u64 v[2:3], v[158:159], 0, v[16:17]
	v_mad_u64_u32 v[4:5], s[12:13], v2, s17, v[10:11]
	v_mad_i32_i24 v5, v3, s17, v5
	v_lshl_add_u64 v[2:3], v[4:5], 0, v[12:13]
	v_lshl_add_u64 v[2:3], v[2:3], 0, v[128:129]
	s_waitcnt lgkmcnt(0)
; template <int EPI, int PN>
; __device__ void gemm_phase(const Params& p, const u16* __restrict__ A, const u16* __restrict__ Bt, int nNt, char* smem) {
;     ...
;       for (int it = 0; it < 16; ++it) {
;         const int c = it * 64 + laneE, row = c >> 3, seg = c & 7;
;         const uint4 v = *(const uint4*)(et + row * 144 + seg * 16);
;         if (EPI == 0) *(uint4*)(p.proj + (row0 + row) * NPROJ + col0 + seg * 8) = v;
;         else *(uint4*)(p.qp + (row0 + row) * DM + col0 + seg * 8) = v;
;       }
	global_store_dwordx4 v[2:3], v[6:9], off sc1
	v_readlane_b32 s46, v253, 49
	v_readlane_b32 s47, v253, 50
	v_ashrrev_i32_e32 v6, 3, v1
	v_mad_u64_u32 v[2:3], s[12:13], v6, s16, v[0:1]
	v_ashrrev_i32_e32 v7, 31, v6
	ds_read_b128 v[2:5], v2
	v_lshl_add_u64 v[6:7], v[158:159], 0, v[6:7]
	v_mad_u64_u32 v[8:9], s[12:13], v6, s17, v[10:11]
	v_mad_i32_i24 v9, v7, s17, v9
	v_add_u32_e32 v1, 0x1c0, v177
	v_lshl_add_u64 v[6:7], v[8:9], 0, v[12:13]
	v_ashrrev_i32_e32 v16, 3, v1
	v_lshl_add_u64 v[14:15], v[6:7], 0, v[128:129]
	v_mad_u64_u32 v[6:7], s[12:13], v16, s16, v[0:1]
	v_ashrrev_i32_e32 v17, 31, v16
	ds_read_b128 v[6:9], v6
	s_waitcnt lgkmcnt(1)
	global_store_dwordx4 v[14:15], v[2:5], off sc1
	v_add_u32_e32 v1, 0x200, v177
	v_readlane_b32 s48, v253, 51
	v_lshl_add_u64 v[2:3], v[158:159], 0, v[16:17]
	v_mad_u64_u32 v[4:5], s[12:13], v2, s17, v[10:11]
	v_mad_i32_i24 v5, v3, s17, v5
	v_lshl_add_u64 v[2:3], v[4:5], 0, v[12:13]
	v_lshl_add_u64 v[2:3], v[2:3], 0, v[128:129]
	s_waitcnt lgkmcnt(0)
	global_store_dwordx4 v[2:3], v[6:9], off sc1
	v_readlane_b32 s49, v253, 52
	v_readlane_b32 s50, v253, 53
	v_ashrrev_i32_e32 v6, 3, v1
	v_mad_u64_u32 v[2:3], s[12:13], v6, s16, v[0:1]
	v_ashrrev_i32_e32 v7, 31, v6
	ds_read_b128 v[2:5], v2
	v_lshl_add_u64 v[6:7], v[158:159], 0, v[6:7]
	v_mad_u64_u32 v[8:9], s[12:13], v6, s17, v[10:11]
	v_mad_i32_i24 v9, v7, s17, v9
	v_add_u32_e32 v1, 0x240, v177
	v_lshl_add_u64 v[6:7], v[8:9], 0, v[12:13]
	v_ashrrev_i32_e32 v16, 3, v1
	v_lshl_add_u64 v[14:15], v[6:7], 0, v[128:129]
	v_mad_u64_u32 v[6:7], s[12:13], v16, s16, v[0:1]
	v_ashrrev_i32_e32 v17, 31, v16
	ds_read_b128 v[6:9], v6
	s_waitcnt lgkmcnt(1)
	global_store_dwordx4 v[14:15], v[2:5], off sc1
	v_add_u32_e32 v1, 0x280, v177
	v_readlane_b32 s51, v253, 54
	v_lshl_add_u64 v[2:3], v[158:159], 0, v[16:17]
	v_mad_u64_u32 v[4:5], s[12:13], v2, s17, v[10:11]
	v_mad_i32_i24 v5, v3, s17, v5
	v_lshl_add_u64 v[2:3], v[4:5], 0, v[12:13]
	v_lshl_add_u64 v[2:3], v[2:3], 0, v[128:129]
	s_waitcnt lgkmcnt(0)
	global_store_dwordx4 v[2:3], v[6:9], off sc1
	s_nop 1
	v_ashrrev_i32_e32 v6, 3, v1
	v_mad_u64_u32 v[2:3], s[12:13], v6, s16, v[0:1]
	v_ashrrev_i32_e32 v7, 31, v6
	ds_read_b128 v[2:5], v2
	v_lshl_add_u64 v[6:7], v[158:159], 0, v[6:7]
	v_mad_u64_u32 v[8:9], s[12:13], v6, s17, v[10:11]
	v_mad_i32_i24 v9, v7, s17, v9
	v_add_u32_e32 v1, 0x2c0, v177
	v_lshl_add_u64 v[6:7], v[8:9], 0, v[12:13]
	v_ashrrev_i32_e32 v16, 3, v1
	v_lshl_add_u64 v[14:15], v[6:7], 0, v[128:129]
	v_mad_u64_u32 v[6:7], s[12:13], v16, s16, v[0:1]
	v_ashrrev_i32_e32 v17, 31, v16
	ds_read_b128 v[6:9], v6
	s_waitcnt lgkmcnt(1)
	global_store_dwordx4 v[14:15], v[2:5], off sc1
	v_add_u32_e32 v1, 0x300, v177
	s_nop 0
	v_lshl_add_u64 v[2:3], v[158:159], 0, v[16:17]
	v_mad_u64_u32 v[4:5], s[12:13], v2, s17, v[10:11]
	v_mad_i32_i24 v5, v3, s17, v5
	v_lshl_add_u64 v[2:3], v[4:5], 0, v[12:13]
	v_lshl_add_u64 v[2:3], v[2:3], 0, v[128:129]
	s_waitcnt lgkmcnt(0)
	global_store_dwordx4 v[2:3], v[6:9], off sc1
	s_nop 1
	v_ashrrev_i32_e32 v6, 3, v1
	v_mad_u64_u32 v[2:3], s[12:13], v6, s16, v[0:1]
	v_ashrrev_i32_e32 v7, 31, v6
	ds_read_b128 v[2:5], v2
	v_lshl_add_u64 v[6:7], v[158:159], 0, v[6:7]
	v_mad_u64_u32 v[8:9], s[12:13], v6, s17, v[10:11]
	v_mad_i32_i24 v9, v7, s17, v9
	v_add_u32_e32 v1, 0x340, v177
	v_lshl_add_u64 v[6:7], v[8:9], 0, v[12:13]
	v_ashrrev_i32_e32 v16, 3, v1
	v_lshl_add_u64 v[14:15], v[6:7], 0, v[128:129]
	v_mad_u64_u32 v[6:7], s[12:13], v16, s16, v[0:1]
	v_ashrrev_i32_e32 v17, 31, v16
	ds_read_b128 v[6:9], v6
	s_waitcnt lgkmcnt(1)
	global_store_dwordx4 v[14:15], v[2:5], off sc1
	v_add_u32_e32 v1, 0x380, v177
	s_nop 0
	v_lshl_add_u64 v[2:3], v[158:159], 0, v[16:17]
	v_mad_u64_u32 v[4:5], s[12:13], v2, s17, v[10:11]
	v_mad_i32_i24 v5, v3, s17, v5
	v_lshl_add_u64 v[2:3], v[4:5], 0, v[12:13]
	v_lshl_add_u64 v[2:3], v[2:3], 0, v[128:129]
	s_waitcnt lgkmcnt(0)
	global_store_dwordx4 v[2:3], v[6:9], off sc1
	s_nop 1
	v_ashrrev_i32_e32 v6, 3, v1
	v_mad_u64_u32 v[2:3], s[12:13], v6, s16, v[0:1]
	v_ashrrev_i32_e32 v7, 31, v6
	ds_read_b128 v[2:5], v2
	v_lshl_add_u64 v[6:7], v[158:159], 0, v[6:7]
	v_mad_u64_u32 v[8:9], s[12:13], v6, s17, v[10:11]
	v_add_u32_e32 v1, 0x3c0, v177
	v_mad_i32_i24 v9, v7, s17, v9
	v_ashrrev_i32_e32 v16, 3, v1
	v_lshl_add_u64 v[6:7], v[8:9], 0, v[12:13]
	v_mad_u64_u32 v[0:1], s[12:13], v16, s16, v[0:1]
	v_ashrrev_i32_e32 v17, 31, v16
	v_lshl_add_u64 v[14:15], v[6:7], 0, v[128:129]
	ds_read_b128 v[6:9], v0
	v_lshl_add_u64 v[0:1], v[158:159], 0, v[16:17]
	s_waitcnt lgkmcnt(1)
	global_store_dwordx4 v[14:15], v[2:5], off sc1
	s_nop 1
	v_mad_u64_u32 v[2:3], s[12:13], v0, s17, v[10:11]
	v_mad_i32_i24 v3, v1, s17, v3
	v_lshl_add_u64 v[0:1], v[2:3], 0, v[12:13]
	v_lshl_add_u64 v[0:1], v[0:1], 0, v[128:129]
	s_waitcnt lgkmcnt(0)
	global_store_dwordx4 v[0:1], v[6:9], off sc1

; template <int EPI, int PN>
; __device__ void gemm_phase(const Params& p, const u16* __restrict__ A, const u16* __restrict__ Bt, int nNt, char* smem) {
;     ...
;     for (int kt = 0; kt < 32; ++kt) {
;       asm volatile("s_waitcnt vmcnt(0)" ::: "memory");
;       __builtin_amdgcn_s_barrier();
;       const u16* Ab = ring + (kt & 1) * STG;
;       const u16* Bb = Ab + 16384;
;       u16* st = ring + ((kt + 1) & 1) * STG;
;       const bool pre = (kt + 1 < 32);
;       s16x8 af[2][4], bf[2][2];
;       auto ldfrag = [&](int ks, int slot) {
; #pragma unroll
;         for (int i = 0; i < 4; ++i) {
;           const int row = wr * 128 + i * 32 + lr;
;           af[slot][i] = *(const s16x8*)(Ab + row * 64 + (((ks * 2 + lh) ^ ((row >> 1) & 7)) * 8));
;         }
; #pragma unroll
;         for (int j = 0; j < 2; ++j) {
;           const int rowb = nh * 128 + wc * 64 + j * 32 + lr;
;           bf[slot][j] = *(const s16x8*)(Bb + rowb * 64 + (((ks * 2 + lh) ^ ((rowb >> 1) & 7)) * 8));
;         }
;       };
;       ldfrag(0, 0);
;       ldfrag(1, 1);
;       __builtin_amdgcn_sched_barrier(0);
; #pragma unroll
;       for (int ks = 0; ks < 4; ++ks) {
;         const int slot = ks & 1;
; #pragma unroll
;         for (int i = 0; i < 4; ++i) {
;           acc[i][0] = mfma32(af[slot][i], bf[slot][0], acc[i][0]);
;           acc[i][1] = mfma32(af[slot][i], bf[slot][1], acc[i][1]);
;           __builtin_amdgcn_sched_barrier(0);
;           if (pre && (i & 1) == 0) {
;             const int pi = ks * 2 + (i >> 1);
;             if (pi < 4) glds16(Ag0 + (size_t)pi * 64 * LDK + (kt + 1) * 64, st + (srow + 64 * pi) * 64 + sch * 8);
;             else glds16(Bg0 + (size_t)(pi - 4) * 64 * LDK + (kt + 1) * 64, st + 16384 + (srow + 64 * (pi - 4)) * 64 + sch * 8);
;             __builtin_amdgcn_sched_barrier(0);
;           }
;         }
;         if (ks + 2 < 4) { ldfrag(ks + 2, slot); __builtin_amdgcn_sched_barrier(0); }
;       }
.Lrot666_loop:
	s_add_i32 s18, s17, 0xffff8000
	s_and_b32 s18, s18, 0x8000
	s_lshl_b32 s18, s18, 1
	v_lshl_or_b32 v128, v143, 1, s18
	v_lshl_add_u32 v166, v147, 1, s18
	s_and_b32 s98, s17, 0x8000
	s_lshl_b32 s98, s98, 1
	s_waitcnt lgkmcnt(7)
	v_mfma_f32_32x32x16_bf16 v[112:127], v[162:165], v[180:183], v[112:127]
	v_add3_u32 v148, s98, v224, v156
	s_waitcnt lgkmcnt(6)
	v_mfma_f32_32x32x16_bf16 v[48:63], v[162:165], v[184:187], v[48:63]
	v_readfirstlane_b32 s100, v148
	s_mov_b32 s19, m0
	s_add_i32 m0, s100, 0x8000
	s_nop 0
	global_load_lds_dwordx4 v[160:161], off
	v_mfma_f32_32x32x16_bf16 v[96:111], v[168:171], v[180:183], v[96:111]
	v_lshl_add_u64 v[162:163], v[160:161], 0, s[4:5]
	s_add_i32 m0, s100, 0xa000
	s_nop 0
	global_load_lds_dwordx4 v[162:163], off
	v_mfma_f32_32x32x16_bf16 v[32:47], v[168:171], v[184:187], v[32:47]
	v_lshl_add_u64 v[164:165], v[160:161], 0, s[6:7]
	s_add_i32 m0, s100, 0xc000
	s_nop 0
	global_load_lds_dwordx4 v[164:165], off
	v_mfma_f32_32x32x16_bf16 v[80:95], v[172:175], v[180:183], v[80:95]
	v_lshl_add_u64 v[162:163], v[160:161], 0, s[8:9]
	s_add_i32 m0, s100, 0xe000
	s_nop 0
	global_load_lds_dwordx4 v[162:163], off
	s_mov_b32 m0, s19
	v_mfma_f32_32x32x16_bf16 v[16:31], v[172:175], v[184:187], v[16:31]
	v_mfma_f32_32x32x16_bf16 v[64:79], v[176:179], v[180:183], v[64:79]
	v_mfma_f32_32x32x16_bf16 v[0:15], v[176:179], v[184:187], v[0:15]
	v_lshl_add_u64 v[160:161], v[160:161], 0, s[10:11]
	v_add_u32_e32 v176, v128, v236
	ds_read_b128 v[162:165], v176
	ds_read_b128 v[168:171], v176 offset:4096
	ds_read_b128 v[172:175], v176 offset:8192
	ds_read_b128 v[176:179], v176 offset:12288
	v_add_u32_e32 v184, v166, v236
	ds_read_b128 v[180:183], v184 offset:32768
	ds_read_b128 v[184:187], v184 offset:36864
	s_waitcnt lgkmcnt(7)
	v_mfma_f32_32x32x16_bf16 v[112:127], v[188:191], v[204:207], v[112:127]
	s_waitcnt lgkmcnt(6)
	v_mfma_f32_32x32x16_bf16 v[48:63], v[188:191], v[208:211], v[48:63]
	v_mfma_f32_32x32x16_bf16 v[96:111], v[192:195], v[204:207], v[96:111]
	v_mfma_f32_32x32x16_bf16 v[32:47], v[192:195], v[208:211], v[32:47]
	v_mfma_f32_32x32x16_bf16 v[80:95], v[196:199], v[204:207], v[80:95]
	v_mfma_f32_32x32x16_bf16 v[16:31], v[196:199], v[208:211], v[16:31]
	v_mfma_f32_32x32x16_bf16 v[64:79], v[200:203], v[204:207], v[64:79]
	v_mfma_f32_32x32x16_bf16 v[0:15], v[200:203], v[208:211], v[0:15]
	v_add_u32_e32 v128, v128, v237
	ds_read_b128 v[188:191], v128
	ds_read_b128 v[192:195], v128 offset:4096
	ds_read_b128 v[196:199], v128 offset:8192
	ds_read_b128 v[200:203], v128 offset:12288
	v_add_u32_e32 v128, v166, v237
	ds_read_b128 v[204:207], v128 offset:32768
	ds_read_b128 v[208:211], v128 offset:36864
	s_waitcnt lgkmcnt(7)
	v_mfma_f32_32x32x16_bf16 v[112:127], v[162:165], v[180:183], v[112:127]
	s_waitcnt lgkmcnt(6)
	v_mfma_f32_32x32x16_bf16 v[48:63], v[162:165], v[184:187], v[48:63]
	v_mfma_f32_32x32x16_bf16 v[96:111], v[168:171], v[180:183], v[96:111]
	v_mfma_f32_32x32x16_bf16 v[32:47], v[168:171], v[184:187], v[32:47]
	v_mfma_f32_32x32x16_bf16 v[80:95], v[172:175], v[180:183], v[80:95]
	v_mfma_f32_32x32x16_bf16 v[16:31], v[172:175], v[184:187], v[16:31]
	v_mfma_f32_32x32x16_bf16 v[64:79], v[176:179], v[180:183], v[64:79]
	v_mfma_f32_32x32x16_bf16 v[0:15], v[176:179], v[184:187], v[0:15]
	v_lshl_or_b32 v212, v143, 1, s98
	v_lshl_add_u32 v213, v147, 1, s98
	v_add_u32_e32 v149, v212, v234
	v_add_u32_e32 v148, v213, v234
	s_waitcnt vmcnt(0) lgkmcnt(0)
	s_barrier
	ds_read_b128 v[162:165], v149
	ds_read_b128 v[168:171], v149 offset:4096
	ds_read_b128 v[172:175], v149 offset:8192
	ds_read_b128 v[176:179], v149 offset:12288
	ds_read_b128 v[180:183], v148 offset:32768
	ds_read_b128 v[184:187], v148 offset:36864
	v_add3_u32 v148, s18, v224, v156
	v_mfma_f32_32x32x16_bf16 v[112:127], v[188:191], v[204:207], v[112:127]
	v_readfirstlane_b32 s99, v148
	s_mov_b32 s19, m0
	s_mov_b32 m0, s99
	s_nop 0
	global_load_lds_dwordx4 v[158:159], off
	v_mfma_f32_32x32x16_bf16 v[48:63], v[188:191], v[208:211], v[48:63]
	v_lshl_add_u64 v[188:189], v[158:159], 0, s[4:5]
	s_add_i32 m0, s99, 0x2000
	s_nop 0
	global_load_lds_dwordx4 v[188:189], off
	v_mfma_f32_32x32x16_bf16 v[96:111], v[192:195], v[204:207], v[96:111]
	v_lshl_add_u64 v[190:191], v[158:159], 0, s[6:7]
	s_add_i32 m0, s99, 0x4000
	s_nop 0
	global_load_lds_dwordx4 v[190:191], off
	v_mfma_f32_32x32x16_bf16 v[32:47], v[192:195], v[208:211], v[32:47]
	v_lshl_add_u64 v[188:189], v[158:159], 0, s[8:9]
	s_add_i32 m0, s99, 0x6000
	s_nop 0
	global_load_lds_dwordx4 v[188:189], off
	s_mov_b32 m0, s19
	v_mfma_f32_32x32x16_bf16 v[80:95], v[196:199], v[204:207], v[80:95]
	v_mfma_f32_32x32x16_bf16 v[16:31], v[196:199], v[208:211], v[16:31]
	v_mfma_f32_32x32x16_bf16 v[64:79], v[200:203], v[204:207], v[64:79]
	v_mfma_f32_32x32x16_bf16 v[0:15], v[200:203], v[208:211], v[0:15]
	v_add_u32_e32 v149, v212, v235
	v_add_u32_e32 v148, v213, v235
	ds_read_b128 v[188:191], v149
	ds_read_b128 v[192:195], v149 offset:4096
	ds_read_b128 v[196:199], v149 offset:8192
	ds_read_b128 v[200:203], v149 offset:12288
	ds_read_b128 v[204:207], v148 offset:32768
	ds_read_b128 v[208:211], v148 offset:36864
	s_add_i32 s17, s17, 0x8000
	v_lshl_add_u64 v[158:159], v[158:159], 0, s[10:11]
	s_cmp_eq_u32 s17, 0xf8000
	s_cbranch_scc0 .Lrot666_loop
; template <int EPI, int PN>
; __device__ void gemm_phase(const Params& p, const u16* __restrict__ A, const u16* __restrict__ Bt, int nNt, char* smem) {
;     ...
;     for (int kt = 0; kt < 32; ++kt) {
;       asm volatile("s_waitcnt vmcnt(0)" ::: "memory");
;       __builtin_amdgcn_s_barrier();
;       const u16* Ab = ring + (kt & 1) * STG;
;       const u16* Bb = Ab + 16384;
;       u16* st = ring + ((kt + 1) & 1) * STG;
;       const bool pre = (kt + 1 < 32);
;       s16x8 af[2][4], bf[2][2];
;       auto ldfrag = [&](int ks, int slot) {
; #pragma unroll
;         for (int i = 0; i < 4; ++i) {
;           const int row = wr * 128 + i * 32 + lr;
;           af[slot][i] = *(const s16x8*)(Ab + row * 64 + (((ks * 2 + lh) ^ ((row >> 1) & 7)) * 8));
;         }
; #pragma unroll
;         for (int j = 0; j < 2; ++j) {
;           const int rowb = nh * 128 + wc * 64 + j * 32 + lr;
;           bf[slot][j] = *(const s16x8*)(Bb + rowb * 64 + (((ks * 2 + lh) ^ ((rowb >> 1) & 7)) * 8));
;         }
;       };
;       ldfrag(0, 0);
;       ldfrag(1, 1);
;       __builtin_amdgcn_sched_barrier(0);
; #pragma unroll
;       for (int ks = 0; ks < 4; ++ks) {
;         const int slot = ks & 1;
; #pragma unroll
;         for (int i = 0; i < 4; ++i) {
;           acc[i][0] = mfma32(af[slot][i], bf[slot][0], acc[i][0]);
;           acc[i][1] = mfma32(af[slot][i], bf[slot][1], acc[i][1]);
;           __builtin_amdgcn_sched_barrier(0);
;           if (pre && (i & 1) == 0) {
;             const int pi = ks * 2 + (i >> 1);
;             if (pi < 4) glds16(Ag0 + (size_t)pi * 64 * LDK + (kt + 1) * 64, st + (srow + 64 * pi) * 64 + sch * 8);
;             else glds16(Bg0 + (size_t)(pi - 4) * 64 * LDK + (kt + 1) * 64, st + 16384 + (srow + 64 * (pi - 4)) * 64 + sch * 8);
;             __builtin_amdgcn_sched_barrier(0);
;           }
;         }
;         if (ks + 2 < 4) { ldfrag(ks + 2, slot); __builtin_amdgcn_sched_barrier(0); }
;       }
	s_add_i32 s18, s17, 0xffff8000
	s_and_b32 s18, s18, 0x8000
	s_lshl_b32 s18, s18, 1
	v_lshl_or_b32 v128, v143, 1, s18
	v_lshl_add_u32 v166, v147, 1, s18
	s_and_b32 s98, s17, 0x8000
	s_lshl_b32 s98, s98, 1
	s_waitcnt lgkmcnt(7)
	v_mfma_f32_32x32x16_bf16 v[112:127], v[162:165], v[180:183], v[112:127]
	v_add3_u32 v148, s98, v224, v156
	s_waitcnt lgkmcnt(6)
	v_mfma_f32_32x32x16_bf16 v[48:63], v[162:165], v[184:187], v[48:63]
	v_readfirstlane_b32 s100, v148
	s_mov_b32 s19, m0
	s_add_i32 m0, s100, 0x8000
	s_nop 0
	global_load_lds_dwordx4 v[160:161], off
	v_mfma_f32_32x32x16_bf16 v[96:111], v[168:171], v[180:183], v[96:111]
	v_lshl_add_u64 v[162:163], v[160:161], 0, s[4:5]
	s_add_i32 m0, s100, 0xa000
	s_nop 0
	global_load_lds_dwordx4 v[162:163], off
	v_mfma_f32_32x32x16_bf16 v[32:47], v[168:171], v[184:187], v[32:47]
	v_lshl_add_u64 v[164:165], v[160:161], 0, s[6:7]
	s_add_i32 m0, s100, 0xc000
	s_nop 0
	global_load_lds_dwordx4 v[164:165], off
	v_mfma_f32_32x32x16_bf16 v[80:95], v[172:175], v[180:183], v[80:95]
	v_lshl_add_u64 v[162:163], v[160:161], 0, s[8:9]
	s_add_i32 m0, s100, 0xe000
	s_nop 0
	global_load_lds_dwordx4 v[162:163], off
	s_mov_b32 m0, s19
	v_mfma_f32_32x32x16_bf16 v[16:31], v[172:175], v[184:187], v[16:31]
	v_mfma_f32_32x32x16_bf16 v[64:79], v[176:179], v[180:183], v[64:79]
	v_mfma_f32_32x32x16_bf16 v[0:15], v[176:179], v[184:187], v[0:15]
	v_lshl_add_u64 v[160:161], v[160:161], 0, s[10:11]
	v_add_u32_e32 v176, v128, v236
	ds_read_b128 v[162:165], v176
	ds_read_b128 v[168:171], v176 offset:4096
	ds_read_b128 v[172:175], v176 offset:8192
	ds_read_b128 v[176:179], v176 offset:12288
	v_add_u32_e32 v184, v166, v236
	ds_read_b128 v[180:183], v184 offset:32768
	ds_read_b128 v[184:187], v184 offset:36864
	s_waitcnt lgkmcnt(7)
	v_mfma_f32_32x32x16_bf16 v[112:127], v[188:191], v[204:207], v[112:127]
	s_waitcnt lgkmcnt(6)
	v_mfma_f32_32x32x16_bf16 v[48:63], v[188:191], v[208:211], v[48:63]
	v_mfma_f32_32x32x16_bf16 v[96:111], v[192:195], v[204:207], v[96:111]
	v_mfma_f32_32x32x16_bf16 v[32:47], v[192:195], v[208:211], v[32:47]
	v_mfma_f32_32x32x16_bf16 v[80:95], v[196:199], v[204:207], v[80:95]
	v_mfma_f32_32x32x16_bf16 v[16:31], v[196:199], v[208:211], v[16:31]
	v_mfma_f32_32x32x16_bf16 v[64:79], v[200:203], v[204:207], v[64:79]
	v_mfma_f32_32x32x16_bf16 v[0:15], v[200:203], v[208:211], v[0:15]
	v_add_u32_e32 v128, v128, v237
	ds_read_b128 v[188:191], v128
	ds_read_b128 v[192:195], v128 offset:4096
	ds_read_b128 v[196:199], v128 offset:8192
	ds_read_b128 v[200:203], v128 offset:12288
	v_add_u32_e32 v128, v166, v237
	ds_read_b128 v[204:207], v128 offset:32768
	ds_read_b128 v[208:211], v128 offset:36864
	s_waitcnt lgkmcnt(7)
	v_mfma_f32_32x32x16_bf16 v[112:127], v[162:165], v[180:183], v[112:127]
	s_waitcnt lgkmcnt(6)
	v_mfma_f32_32x32x16_bf16 v[48:63], v[162:165], v[184:187], v[48:63]
	v_mfma_f32_32x32x16_bf16 v[96:111], v[168:171], v[180:183], v[96:111]
	v_mfma_f32_32x32x16_bf16 v[32:47], v[168:171], v[184:187], v[32:47]
	v_mfma_f32_32x32x16_bf16 v[80:95], v[172:175], v[180:183], v[80:95]
	v_mfma_f32_32x32x16_bf16 v[16:31], v[172:175], v[184:187], v[16:31]
	v_mfma_f32_32x32x16_bf16 v[64:79], v[176:179], v[180:183], v[64:79]
	v_mfma_f32_32x32x16_bf16 v[0:15], v[176:179], v[184:187], v[0:15]
	s_waitcnt lgkmcnt(1)
	v_mfma_f32_32x32x16_bf16 v[112:127], v[188:191], v[204:207], v[112:127]
	s_waitcnt lgkmcnt(0)
	v_mfma_f32_32x32x16_bf16 v[48:63], v[188:191], v[208:211], v[48:63]
	v_mfma_f32_32x32x16_bf16 v[96:111], v[192:195], v[204:207], v[96:111]
	v_mfma_f32_32x32x16_bf16 v[32:47], v[192:195], v[208:211], v[32:47]
	v_mfma_f32_32x32x16_bf16 v[80:95], v[196:199], v[204:207], v[80:95]
	v_mfma_f32_32x32x16_bf16 v[16:31], v[196:199], v[208:211], v[16:31]
	v_mfma_f32_32x32x16_bf16 v[64:79], v[200:203], v[204:207], v[64:79]
	v_mfma_f32_32x32x16_bf16 v[0:15], v[200:203], v[208:211], v[0:15]
	s_waitcnt vmcnt(0)
	s_barrier
	ds_read_b128 v[158:161], v226
	ds_read_b128 v[162:165], v226 offset:4096
	ds_read_b128 v[168:171], v226 offset:8192
	ds_read_b128 v[172:175], v226 offset:12288
	ds_read_b128 v[176:179], v227
	ds_read_b128 v[180:183], v227 offset:4096
	ds_read_b128 v[184:187], v228
	ds_read_b128 v[188:191], v228 offset:4096
	ds_read_b128 v[192:195], v228 offset:8192
	ds_read_b128 v[196:199], v228 offset:12288
	ds_read_b128 v[200:203], v229
	ds_read_b128 v[204:207], v229 offset:4096
	s_waitcnt lgkmcnt(7)
	v_mfma_f32_32x32x16_bf16 v[112:127], v[158:161], v[176:179], v[112:127]
	s_waitcnt lgkmcnt(6)
	v_mfma_f32_32x32x16_bf16 v[48:63], v[158:161], v[180:183], v[48:63]
	v_mfma_f32_32x32x16_bf16 v[96:111], v[162:165], v[176:179], v[96:111]
	v_mfma_f32_32x32x16_bf16 v[32:47], v[162:165], v[180:183], v[32:47]
	v_mfma_f32_32x32x16_bf16 v[80:95], v[168:171], v[176:179], v[80:95]
	v_mfma_f32_32x32x16_bf16 v[16:31], v[168:171], v[180:183], v[16:31]
	v_mfma_f32_32x32x16_bf16 v[64:79], v[172:175], v[176:179], v[64:79]
	v_mfma_f32_32x32x16_bf16 v[0:15], v[172:175], v[180:183], v[0:15]
	ds_read_b128 v[158:161], v230
	ds_read_b128 v[162:165], v230 offset:4096
	ds_read_b128 v[168:171], v230 offset:8192
	ds_read_b128 v[172:175], v230 offset:12288
	ds_read_b128 v[176:179], v231
	ds_read_b128 v[180:183], v231 offset:4096
	s_waitcnt lgkmcnt(7)
	v_mfma_f32_32x32x16_bf16 v[112:127], v[184:187], v[200:203], v[112:127]
	s_waitcnt lgkmcnt(6)
; __device__ __forceinline__ int accrow(int reg, int lh) { return (reg & 3) + 8 * (reg >> 2) + 4 * lh; }
; template <int EPI, int PN>
; __device__ void gemm_phase(const Params& p, const u16* __restrict__ A, const u16* __restrict__ Bt, int nNt, char* smem) {
;     ...
; #pragma unroll
;       for (int j = 0; j < 2; ++j) {
; #pragma unroll
;         for (int i = 0; i < 4; ++i)
; #pragma unroll
;           for (int r = 0; r < 16; ++r) *(float*)(et + (i * 32 + accrow(r, lhE)) * 144 + lrE * 4) = acc[i][j][r];
; #pragma unroll
;         for (int it = 0; it < 16; ++it) {
;           const int c = it * 64 + laneE, row = c >> 3, seg = c & 7;
;           const float4 v = *(const float4*)(et + row * 144 + seg * 16);
;           const size_t g = (row0 + row) * DM + col0 + j * 32 + seg * 4;
;           const float4 xv = *(const float4*)(p.x + g);
	v_mfma_f32_32x32x16_bf16 v[48:63], v[184:187], v[204:207], v[48:63]
	v_mfma_f32_32x32x16_bf16 v[96:111], v[188:191], v[200:203], v[96:111]
	v_mfma_f32_32x32x16_bf16 v[32:47], v[188:191], v[204:207], v[32:47]
	v_mfma_f32_32x32x16_bf16 v[80:95], v[192:195], v[200:203], v[80:95]
	v_mfma_f32_32x32x16_bf16 v[16:31], v[192:195], v[204:207], v[16:31]
	v_mfma_f32_32x32x16_bf16 v[64:79], v[196:199], v[200:203], v[64:79]
	v_mfma_f32_32x32x16_bf16 v[0:15], v[196:199], v[204:207], v[0:15]
	ds_read_b128 v[184:187], v232
	ds_read_b128 v[188:191], v232 offset:4096
	ds_read_b128 v[192:195], v232 offset:8192
	ds_read_b128 v[196:199], v232 offset:12288
	ds_read_b128 v[200:203], v233
	ds_read_b128 v[204:207], v233 offset:4096
	s_waitcnt lgkmcnt(7)
	v_mfma_f32_32x32x16_bf16 v[112:127], v[158:161], v[176:179], v[112:127]
	s_waitcnt lgkmcnt(6)
	v_mfma_f32_32x32x16_bf16 v[48:63], v[158:161], v[180:183], v[48:63]
	v_mfma_f32_32x32x16_bf16 v[96:111], v[162:165], v[176:179], v[96:111]
	v_mfma_f32_32x32x16_bf16 v[32:47], v[162:165], v[180:183], v[32:47]
	v_mfma_f32_32x32x16_bf16 v[80:95], v[168:171], v[176:179], v[80:95]
	v_mfma_f32_32x32x16_bf16 v[16:31], v[168:171], v[180:183], v[16:31]
	v_mfma_f32_32x32x16_bf16 v[64:79], v[172:175], v[176:179], v[64:79]
	v_mfma_f32_32x32x16_bf16 v[0:15], v[172:175], v[180:183], v[0:15]
	s_waitcnt lgkmcnt(1)
	v_mfma_f32_32x32x16_bf16 v[112:127], v[184:187], v[200:203], v[112:127]
	s_waitcnt lgkmcnt(0)
	v_mfma_f32_32x32x16_bf16 v[48:63], v[184:187], v[204:207], v[48:63]
	v_mfma_f32_32x32x16_bf16 v[96:111], v[188:191], v[200:203], v[96:111]
	v_mfma_f32_32x32x16_bf16 v[32:47], v[188:191], v[204:207], v[32:47]
	v_mfma_f32_32x32x16_bf16 v[80:95], v[192:195], v[200:203], v[80:95]
	v_mfma_f32_32x32x16_bf16 v[16:31], v[192:195], v[204:207], v[16:31]
	v_mfma_f32_32x32x16_bf16 v[64:79], v[196:199], v[200:203], v[64:79]
	v_mfma_f32_32x32x16_bf16 v[0:15], v[196:199], v[204:207], v[0:15]
	v_mov_b32_e32 v128, v139
	v_mov_b32_e32 v148, v137
	v_mov_b32_e32 v218, v135
	s_barrier
	v_readlane_b32 s52, v253, 7
	v_lshl_add_u32 v172, s13, 8, v145
	s_ashr_i32 s13, s12, 31
	s_lshl_b64 s[12:13], s[12:13], 8
	v_ashrrev_i32_e32 v158, 3, v218
	v_mov_b32_e32 v163, s13
	v_or_b32_e32 v162, s12, v134
	v_ashrrev_i32_e32 v159, 31, v158
	v_and_b32_e32 v149, 7, v218
	v_ashrrev_i32_e32 v173, 31, v172
	v_lshl_add_u64 v[174:175], v[162:163], 0, v[158:159]
	v_lshl_or_b32 v164, v149, 2, v172
	v_mov_b32_e32 v165, v173
	v_lshlrev_b64 v[160:161], 11, v[174:175]
	v_lshl_add_u64 v[160:161], v[160:161], 0, v[164:165]
	v_lshlrev_b64 v[176:177], 2, v[160:161]
	v_readlane_b32 s53, v253, 8
	v_lshl_add_u32 v166, v149, 4, v225
	v_lshlrev_b32_e32 v148, 2, v148
	v_lshl_add_u64 v[160:161], s[52:53], 0, v[176:177]
	global_load_dwordx4 v[168:171], v[160:161], off
	v_mad_u64_u32 v[158:159], s[12:13], v158, s14, v[166:167]
	v_mul_lo_u32 v128, v128, s15
	v_add3_u32 v159, v225, v148, v128
	ds_write_b32 v159, v112
	ds_write_b32 v159, v113 offset:144
	ds_write_b32 v159, v114 offset:288
	ds_write_b32 v159, v115 offset:432
	ds_write_b32 v159, v116 offset:1152
	ds_write_b32 v159, v117 offset:1296
	ds_write_b32 v159, v118 offset:1440
	ds_write_b32 v159, v119 offset:1584
	ds_write_b32 v159, v120 offset:2304
	ds_write_b32 v159, v121 offset:2448
	ds_write_b32 v159, v122 offset:2592
	ds_write_b32 v159, v123 offset:2736
	ds_write_b32 v159, v124 offset:3456
	ds_write_b32 v159, v125 offset:3600
	ds_write_b32 v159, v126 offset:3744
	ds_write_b32 v159, v127 offset:3888
	ds_write_b32 v159, v96 offset:4608
	ds_write_b32 v159, v97 offset:4752
	ds_write_b32 v159, v98 offset:4896
	ds_write_b32 v159, v99 offset:5040
	ds_write_b32 v159, v100 offset:5760
	ds_write_b32 v159, v101 offset:5904
	ds_write_b32 v159, v102 offset:6048
	ds_write_b32 v159, v103 offset:6192
	ds_write_b32 v159, v104 offset:6912
	ds_write_b32 v159, v105 offset:7056
	ds_write_b32 v159, v106 offset:7200
	ds_write_b32 v159, v107 offset:7344
	ds_write_b32 v159, v108 offset:8064
	ds_write_b32 v159, v109 offset:8208
	ds_write_b32 v159, v110 offset:8352
	ds_write_b32 v159, v111 offset:8496
	ds_write_b32 v159, v80 offset:9216
	ds_write_b32 v159, v81 offset:9360
	ds_write_b32 v159, v82 offset:9504
	ds_write_b32 v159, v83 offset:9648
	ds_write_b32 v159, v84 offset:10368
	ds_write_b32 v159, v85 offset:10512
	ds_write_b32 v159, v86 offset:10656
	ds_write_b32 v159, v87 offset:10800
	ds_write_b32 v159, v88 offset:11520
	ds_write_b32 v159, v89 offset:11664
	ds_write_b32 v159, v90 offset:11808
	ds_write_b32 v159, v91 offset:11952
	ds_write_b32 v159, v92 offset:12672
	ds_write_b32 v159, v93 offset:12816
	ds_write_b32 v159, v94 offset:12960
	ds_write_b32 v159, v95 offset:13104
	ds_write_b32 v159, v64 offset:13824
	ds_write_b32 v159, v65 offset:13968
	ds_write_b32 v159, v66 offset:14112
	ds_write_b32 v159, v67 offset:14256
	ds_write_b32 v159, v68 offset:14976
	ds_write_b32 v159, v69 offset:15120
	ds_write_b32 v159, v70 offset:15264
	ds_write_b32 v159, v71 offset:15408
	ds_write_b32 v159, v72 offset:16128
	ds_write_b32 v159, v73 offset:16272
	ds_write_b32 v159, v74 offset:16416
	ds_write_b32 v159, v75 offset:16560
	ds_write_b32 v159, v76 offset:17280
	ds_write_b32 v159, v77 offset:17424
	ds_write_b32 v159, v78 offset:17568
	ds_write_b32 v159, v79 offset:17712
	ds_read_b128 v[66:69], v158
	v_readlane_b32 s36, v253, 23
	v_readlane_b32 s40, v253, 27
	v_readlane_b32 s41, v253, 28
	v_readlane_b32 s42, v253, 29
	v_readlane_b32 s43, v253, 30
	s_mov_b64 s[20:21], s[40:41]
	s_mov_b64 s[22:23], s[42:43]
	v_lshl_add_u64 v[64:65], s[20:21], 0, v[176:177]
	v_mov_b64_e32 v[102:103], s[22:23]
	v_lshlrev_b64 v[104:105], 1, v[172:173]
	v_lshlrev_b32_e32 v128, 3, v149
	v_readlane_b32 s54, v253, 9
	v_readlane_b32 s55, v253, 10
	v_readlane_b32 s56, v253, 11
	v_readlane_b32 s57, v253, 12
	v_readlane_b32 s58, v253, 13
	v_readlane_b32 s59, v253, 14
	v_readlane_b32 s60, v253, 15
	v_readlane_b32 s61, v253, 16
	v_readlane_b32 s62, v253, 17
	v_readlane_b32 s63, v253, 18
	v_readlane_b32 s64, v253, 19
	v_readlane_b32 s65, v253, 20
	v_readlane_b32 s66, v253, 21
	v_readlane_b32 s67, v253, 22
	v_readlane_b32 s37, v253, 24
	v_readlane_b32 s38, v253, 25
	v_readlane_b32 s39, v253, 26
	v_readlane_b32 s44, v253, 31
	v_readlane_b32 s45, v253, 32
	v_readlane_b32 s46, v253, 33
	v_readlane_b32 s47, v253, 34
	v_readlane_b32 s48, v253, 35
	v_readlane_b32 s49, v253, 36
	v_readlane_b32 s50, v253, 37
	v_readlane_b32 s51, v253, 38
	s_waitcnt vmcnt(0) lgkmcnt(0)
; template <int EPI, int PN>
; __device__ void gemm_phase(const Params& p, const u16* __restrict__ A, const u16* __restrict__ Bt, int nNt, char* smem) {
;     ...
; #pragma unroll
;         for (int it = 0; it < 16; ++it) {
;           const int c = it * 64 + laneE, row = c >> 3, seg = c & 7;
;           const float4 v = *(const float4*)(et + row * 144 + seg * 16);
;           const size_t g = (row0 + row) * DM + col0 + j * 32 + seg * 4;
;           const float4 xv = *(const float4*)(p.x + g);
;           const float4 hv = make_float4(xv.x + v.x, xv.y + v.y, xv.z + v.z, xv.w + v.w);
;           *(float4*)(p.out + g) = hv;
;           uint2 hb; hb.x = pack2(hv.x, hv.y); hb.y = pack2(hv.z, hv.w);
;           *(uint2*)(p.xn + (row0 + row) * LDK + col0 + j * 32 + seg * 4) = hb;
;         }
	v_pk_add_f32 v[66:67], v[66:67], v[168:169]
	v_pk_add_f32 v[68:69], v[68:69], v[170:171]
	global_store_dwordx4 v[64:65], v[66:69], off sc1
	v_cvt_pk_bf16_f32 v70, v66, v67
	v_cvt_pk_bf16_f32 v71, v68, v69
	v_mad_u64_u32 v[66:67], s[12:13], v174, s2, v[102:103]
	v_mad_i32_i24 v67, v175, s2, v67
	v_lshl_add_u64 v[66:67], v[66:67], 0, v[104:105]
	v_lshl_add_u64 v[66:67], v[66:67], 0, v[128:129]
	v_add_u32_e32 v68, 64, v218
	global_store_dwordx2 v[66:67], v[70:71], off
	v_ashrrev_i32_e32 v70, 3, v68
	v_ashrrev_i32_e32 v71, 31, v70
	v_lshl_add_u64 v[74:75], v[162:163], 0, v[70:71]
	v_lshlrev_b64 v[68:69], 11, v[74:75]
	v_lshl_add_u64 v[68:69], v[68:69], 0, v[164:165]
	v_lshlrev_b64 v[76:77], 2, v[68:69]
	v_lshl_add_u64 v[68:69], s[52:53], 0, v[76:77]
	global_load_dwordx4 v[78:81], v[68:69], off
	v_mad_u64_u32 v[72:73], s[12:13], v70, s14, v[166:167]
	v_add_u32_e32 v71, 0x80, v218
	ds_read_b128 v[82:85], v72
	v_ashrrev_i32_e32 v90, 3, v71
	v_ashrrev_i32_e32 v91, 31, v90
	v_lshl_add_u64 v[94:95], v[162:163], 0, v[90:91]
	v_mad_u64_u32 v[70:71], s[12:13], v74, s2, v[102:103]
	v_lshlrev_b64 v[86:87], 11, v[94:95]
	v_mad_i32_i24 v71, v75, s2, v71
	v_lshl_add_u64 v[74:75], v[86:87], 0, v[164:165]
	v_lshl_add_u64 v[70:71], v[70:71], 0, v[104:105]
	v_lshl_add_u64 v[76:77], s[20:21], 0, v[76:77]
	v_lshlrev_b64 v[96:97], 2, v[74:75]
	v_lshl_add_u64 v[74:75], v[70:71], 0, v[128:129]
	v_lshl_add_u64 v[70:71], s[52:53], 0, v[96:97]
	v_add_u32_e32 v73, 0xc0, v218
	v_ashrrev_i32_e32 v98, 3, v73
	v_ashrrev_i32_e32 v99, 31, v98
	v_lshl_add_u64 v[106:107], v[162:163], 0, v[98:99]
	v_add_u32_e32 v73, 0x100, v218
	v_ashrrev_i32_e32 v110, 3, v73
	v_ashrrev_i32_e32 v111, 31, v110
	v_lshl_add_u64 v[114:115], v[162:163], 0, v[110:111]
	v_add_u32_e32 v73, 0x140, v218
	v_ashrrev_i32_e32 v118, 3, v73
	v_ashrrev_i32_e32 v119, 31, v118
	v_lshl_add_u64 v[122:123], v[162:163], 0, v[118:119]
	v_add_u32_e32 v73, 0x180, v218
	v_ashrrev_i32_e32 v126, 3, v73
	v_ashrrev_i32_e32 v127, 31, v126
	v_lshl_add_u64 v[172:173], v[162:163], 0, v[126:127]
	v_add_u32_e32 v73, 0x1c0, v218
	v_ashrrev_i32_e32 v176, 3, v73
	v_ashrrev_i32_e32 v177, 31, v176
	v_add_u32_e32 v73, 0x200, v218
	v_ashrrev_i32_e32 v182, 3, v73
	v_ashrrev_i32_e32 v183, 31, v182
	v_lshl_add_u64 v[186:187], v[162:163], 0, v[182:183]
	v_add_u32_e32 v73, 0x240, v218
	v_ashrrev_i32_e32 v190, 3, v73
	v_ashrrev_i32_e32 v191, 31, v190
	v_lshl_add_u64 v[194:195], v[162:163], 0, v[190:191]
	v_add_u32_e32 v73, 0x280, v218
	v_ashrrev_i32_e32 v198, 3, v73
	v_ashrrev_i32_e32 v199, 31, v198
	v_lshl_add_u64 v[202:203], v[162:163], 0, v[198:199]
	v_add_u32_e32 v73, 0x2c0, v218
	v_ashrrev_i32_e32 v206, 3, v73
	v_ashrrev_i32_e32 v207, 31, v206
	v_lshl_add_u64 v[210:211], v[162:163], 0, v[206:207]
	v_add_u32_e32 v73, 0x300, v218
	v_ashrrev_i32_e32 v214, 3, v73
	v_ashrrev_i32_e32 v215, 31, v214
	v_lshl_add_u64 v[220:221], v[162:163], 0, v[214:215]
	v_add_u32_e32 v73, 0x340, v218
	v_ashrrev_i32_e32 v238, 3, v73
	v_ashrrev_i32_e32 v239, 31, v238
	v_lshl_add_u64 v[242:243], v[162:163], 0, v[238:239]
	v_add_u32_e32 v73, 0x380, v218
	v_ashrrev_i32_e32 v246, 3, v73
	v_ashrrev_i32_e32 v247, 31, v246
	v_lshl_add_u64 v[248:249], v[162:163], 0, v[246:247]
	v_add_u32_e32 v73, 0x3c0, v218
	v_mad_u64_u32 v[218:219], s[12:13], v246, s14, v[166:167]
	v_ashrrev_i32_e32 v148, 3, v73
	v_ashrrev_i32_e32 v149, 31, v148
	v_lshl_add_u64 v[246:247], v[162:163], 0, v[148:149]
	s_waitcnt vmcnt(0) lgkmcnt(0)
	v_pk_add_f32 v[78:79], v[82:83], v[78:79]
	v_pk_add_f32 v[80:81], v[84:85], v[80:81]
	global_store_dwordx4 v[76:77], v[78:81], off sc1
	v_lshlrev_b64 v[82:83], 11, v[106:107]
	v_lshl_add_u64 v[82:83], v[82:83], 0, v[164:165]
	v_cvt_pk_bf16_f32 v78, v78, v79
	v_cvt_pk_bf16_f32 v79, v80, v81
	global_store_dwordx2 v[74:75], v[78:79], off
	global_load_dwordx4 v[86:89], v[70:71], off
	v_mad_u64_u32 v[80:81], s[12:13], v90, s14, v[166:167]
	ds_read_b128 v[90:93], v80
	v_mad_u64_u32 v[78:79], s[12:13], v94, s2, v[102:103]
	v_mad_i32_i24 v79, v95, s2, v79
	v_lshl_add_u64 v[78:79], v[78:79], 0, v[104:105]
	v_lshl_add_u64 v[84:85], s[20:21], 0, v[96:97]
	v_lshlrev_b64 v[108:109], 2, v[82:83]
	v_lshl_add_u64 v[82:83], v[78:79], 0, v[128:129]
	v_lshl_add_u64 v[78:79], s[52:53], 0, v[108:109]
	s_waitcnt vmcnt(0) lgkmcnt(0)
	v_pk_add_f32 v[86:87], v[90:91], v[86:87]
	v_pk_add_f32 v[88:89], v[92:93], v[88:89]
	global_store_dwordx4 v[84:85], v[86:89], off sc1
	v_lshlrev_b64 v[90:91], 11, v[114:115]
	v_lshl_add_u64 v[90:91], v[90:91], 0, v[164:165]
	v_cvt_pk_bf16_f32 v86, v86, v87
	v_cvt_pk_bf16_f32 v87, v88, v89
	global_store_dwordx2 v[82:83], v[86:87], off
	global_load_dwordx4 v[94:97], v[78:79], off
	v_mad_u64_u32 v[88:89], s[12:13], v98, s14, v[166:167]
	ds_read_b128 v[98:101], v88
	v_mad_u64_u32 v[86:87], s[12:13], v106, s2, v[102:103]
	v_mad_i32_i24 v87, v107, s2, v87
	v_lshl_add_u64 v[86:87], v[86:87], 0, v[104:105]
	v_lshl_add_u64 v[92:93], s[20:21], 0, v[108:109]
	v_lshlrev_b64 v[116:117], 2, v[90:91]
	v_lshl_add_u64 v[90:91], v[86:87], 0, v[128:129]
	v_lshl_add_u64 v[86:87], s[52:53], 0, v[116:117]
	s_waitcnt vmcnt(0) lgkmcnt(0)
	v_pk_add_f32 v[94:95], v[98:99], v[94:95]
	v_pk_add_f32 v[96:97], v[100:101], v[96:97]
	global_store_dwordx4 v[92:93], v[94:97], off sc1
	v_lshlrev_b64 v[98:99], 11, v[122:123]
	v_lshl_add_u64 v[98:99], v[98:99], 0, v[164:165]
	v_cvt_pk_bf16_f32 v94, v94, v95
	v_cvt_pk_bf16_f32 v95, v96, v97
	global_store_dwordx2 v[90:91], v[94:95], off
	global_load_dwordx4 v[106:109], v[86:87], off
	v_mad_u64_u32 v[96:97], s[12:13], v110, s14, v[166:167]
	ds_read_b128 v[110:113], v96
	v_mad_u64_u32 v[94:95], s[12:13], v114, s2, v[102:103]
	v_mad_i32_i24 v95, v115, s2, v95
	v_lshl_add_u64 v[94:95], v[94:95], 0, v[104:105]
	v_lshl_add_u64 v[100:101], s[20:21], 0, v[116:117]
	v_lshlrev_b64 v[124:125], 2, v[98:99]
	v_lshl_add_u64 v[98:99], v[94:95], 0, v[128:129]
	v_lshl_add_u64 v[94:95], s[52:53], 0, v[124:125]
	s_waitcnt vmcnt(0) lgkmcnt(0)
; template <int EPI, int PN>
; __device__ void gemm_phase(const Params& p, const u16* __restrict__ A, const u16* __restrict__ Bt, int nNt, char* smem) {
;     ...
; #pragma unroll
;         for (int it = 0; it < 16; ++it) {
;           const int c = it * 64 + laneE, row = c >> 3, seg = c & 7;
;           const float4 v = *(const float4*)(et + row * 144 + seg * 16);
;           const size_t g = (row0 + row) * DM + col0 + j * 32 + seg * 4;
;           const float4 xv = *(const float4*)(p.x + g);
;           const float4 hv = make_float4(xv.x + v.x, xv.y + v.y, xv.z + v.z, xv.w + v.w);
;           *(float4*)(p.out + g) = hv;
;           uint2 hb; hb.x = pack2(hv.x, hv.y); hb.y = pack2(hv.z, hv.w);
;           *(uint2*)(p.xn + (row0 + row) * LDK + col0 + j * 32 + seg * 4) = hb;
;         }
	v_pk_add_f32 v[106:107], v[110:111], v[106:107]
	v_pk_add_f32 v[108:109], v[112:113], v[108:109]
	global_store_dwordx4 v[100:101], v[106:109], off sc1
	v_lshlrev_b64 v[110:111], 11, v[172:173]
	v_lshl_add_u64 v[110:111], v[110:111], 0, v[164:165]
	v_cvt_pk_bf16_f32 v106, v106, v107
	v_cvt_pk_bf16_f32 v107, v108, v109
	global_store_dwordx2 v[98:99], v[106:107], off
	global_load_dwordx4 v[114:117], v[94:95], off
	v_mad_u64_u32 v[108:109], s[12:13], v118, s14, v[166:167]
	ds_read_b128 v[118:121], v108
	v_mad_u64_u32 v[106:107], s[12:13], v122, s2, v[102:103]
	v_mad_i32_i24 v107, v123, s2, v107
	v_lshl_add_u64 v[106:107], v[106:107], 0, v[104:105]
	v_lshl_add_u64 v[112:113], s[20:21], 0, v[124:125]
	v_lshlrev_b64 v[174:175], 2, v[110:111]
	v_lshl_add_u64 v[110:111], v[106:107], 0, v[128:129]
	v_lshl_add_u64 v[106:107], s[52:53], 0, v[174:175]
	s_waitcnt vmcnt(0) lgkmcnt(0)
	v_pk_add_f32 v[114:115], v[118:119], v[114:115]
	v_pk_add_f32 v[116:117], v[120:121], v[116:117]
	global_store_dwordx4 v[112:113], v[114:117], off sc1
	v_lshl_add_u64 v[120:121], s[20:21], 0, v[174:175]
	s_nop 0
	v_cvt_pk_bf16_f32 v114, v114, v115
	v_cvt_pk_bf16_f32 v115, v116, v117
	global_store_dwordx2 v[110:111], v[114:115], off
	global_load_dwordx4 v[122:125], v[106:107], off
	v_mad_u64_u32 v[116:117], s[12:13], v126, s14, v[166:167]
	ds_read_b128 v[168:171], v116
	v_lshl_add_u64 v[126:127], v[162:163], 0, v[176:177]
	v_mad_u64_u32 v[114:115], s[12:13], v172, s2, v[102:103]
	v_lshlrev_b64 v[118:119], 11, v[126:127]
	v_mad_i32_i24 v115, v173, s2, v115
	v_lshl_add_u64 v[118:119], v[118:119], 0, v[164:165]
	v_lshl_add_u64 v[114:115], v[114:115], 0, v[104:105]
	v_lshlrev_b64 v[178:179], 2, v[118:119]
	v_lshl_add_u64 v[118:119], v[114:115], 0, v[128:129]
	v_lshl_add_u64 v[114:115], s[52:53], 0, v[178:179]
	v_mad_u64_u32 v[162:163], s[12:13], v248, s2, v[102:103]
	v_mad_i32_i24 v163, v249, s2, v163
	v_lshl_add_u64 v[162:163], v[162:163], 0, v[104:105]
	s_waitcnt vmcnt(0) lgkmcnt(0)
	v_pk_add_f32 v[122:123], v[168:169], v[122:123]
	v_pk_add_f32 v[124:125], v[170:171], v[124:125]
	global_store_dwordx4 v[120:121], v[122:125], off sc1
	v_lshlrev_b64 v[168:169], 11, v[186:187]
	s_nop 0
	v_cvt_pk_bf16_f32 v122, v122, v123
	v_cvt_pk_bf16_f32 v123, v124, v125
	global_store_dwordx2 v[118:119], v[122:123], off
	global_load_dwordx4 v[170:173], v[114:115], off
	v_mad_u64_u32 v[124:125], s[12:13], v176, s14, v[166:167]
	ds_read_b128 v[174:177], v124
	v_mad_u64_u32 v[122:123], s[12:13], v126, s2, v[102:103]
	v_mad_i32_i24 v123, v127, s2, v123
	v_lshl_add_u64 v[126:127], v[168:169], 0, v[164:165]
	v_lshl_add_u64 v[122:123], v[122:123], 0, v[104:105]
	v_lshl_add_u64 v[168:169], s[20:21], 0, v[178:179]
	v_lshlrev_b64 v[188:189], 2, v[126:127]
	v_lshl_add_u64 v[126:127], v[122:123], 0, v[128:129]
	v_lshl_add_u64 v[122:123], s[52:53], 0, v[188:189]
	s_waitcnt vmcnt(0) lgkmcnt(0)
	v_pk_add_f32 v[170:171], v[174:175], v[170:171]
	v_pk_add_f32 v[172:173], v[176:177], v[172:173]
	global_store_dwordx4 v[168:169], v[170:173], off sc1
	v_lshlrev_b64 v[174:175], 11, v[194:195]
	v_lshl_add_u64 v[174:175], v[174:175], 0, v[164:165]
	v_cvt_pk_bf16_f32 v170, v170, v171
	v_cvt_pk_bf16_f32 v171, v172, v173
	global_store_dwordx2 v[126:127], v[170:171], off
	global_load_dwordx4 v[178:181], v[122:123], off
	v_mad_u64_u32 v[172:173], s[12:13], v182, s14, v[166:167]
	ds_read_b128 v[182:185], v172
	v_mad_u64_u32 v[170:171], s[12:13], v186, s2, v[102:103]
	v_mad_i32_i24 v171, v187, s2, v171
	v_lshl_add_u64 v[170:171], v[170:171], 0, v[104:105]
	v_lshl_add_u64 v[176:177], s[20:21], 0, v[188:189]
	v_lshlrev_b64 v[196:197], 2, v[174:175]
	v_lshl_add_u64 v[174:175], v[170:171], 0, v[128:129]
	v_lshl_add_u64 v[170:171], s[52:53], 0, v[196:197]
	s_waitcnt vmcnt(0) lgkmcnt(0)
	v_pk_add_f32 v[178:179], v[182:183], v[178:179]
	v_pk_add_f32 v[180:181], v[184:185], v[180:181]
	global_store_dwordx4 v[176:177], v[178:181], off sc1
	v_lshlrev_b64 v[182:183], 11, v[202:203]
	v_lshl_add_u64 v[182:183], v[182:183], 0, v[164:165]
	v_cvt_pk_bf16_f32 v178, v178, v179
	v_cvt_pk_bf16_f32 v179, v180, v181
	global_store_dwordx2 v[174:175], v[178:179], off
	global_load_dwordx4 v[186:189], v[170:171], off
	v_mad_u64_u32 v[180:181], s[12:13], v190, s14, v[166:167]
	ds_read_b128 v[190:193], v180
	v_mad_u64_u32 v[178:179], s[12:13], v194, s2, v[102:103]
	v_mad_i32_i24 v179, v195, s2, v179
	v_lshl_add_u64 v[178:179], v[178:179], 0, v[104:105]
	v_lshl_add_u64 v[184:185], s[20:21], 0, v[196:197]
	v_lshlrev_b64 v[204:205], 2, v[182:183]
	v_lshl_add_u64 v[182:183], v[178:179], 0, v[128:129]
	v_lshl_add_u64 v[178:179], s[52:53], 0, v[204:205]
	s_waitcnt vmcnt(0) lgkmcnt(0)
	v_pk_add_f32 v[186:187], v[190:191], v[186:187]
	v_pk_add_f32 v[188:189], v[192:193], v[188:189]
	global_store_dwordx4 v[184:185], v[186:189], off sc1
	v_lshlrev_b64 v[190:191], 11, v[210:211]
	v_lshl_add_u64 v[190:191], v[190:191], 0, v[164:165]
	v_cvt_pk_bf16_f32 v186, v186, v187
	v_cvt_pk_bf16_f32 v187, v188, v189
	global_store_dwordx2 v[182:183], v[186:187], off
	global_load_dwordx4 v[194:197], v[178:179], off
	v_mad_u64_u32 v[188:189], s[12:13], v198, s14, v[166:167]
	ds_read_b128 v[198:201], v188
	v_mad_u64_u32 v[186:187], s[12:13], v202, s2, v[102:103]
	v_mad_i32_i24 v187, v203, s2, v187
	v_lshl_add_u64 v[186:187], v[186:187], 0, v[104:105]
	v_lshl_add_u64 v[192:193], s[20:21], 0, v[204:205]
	v_lshlrev_b64 v[212:213], 2, v[190:191]
	v_lshl_add_u64 v[190:191], v[186:187], 0, v[128:129]
	v_lshl_add_u64 v[186:187], s[52:53], 0, v[212:213]
	s_waitcnt vmcnt(0) lgkmcnt(0)
; template <int EPI, int PN>
; __device__ void gemm_phase(const Params& p, const u16* __restrict__ A, const u16* __restrict__ Bt, int nNt, char* smem) {
;     ...
;   for (int q = jb;; q += NJ) {
;     const int pl = q / (4 * PN), w = q % (4 * PN);
;     const int gp = pl * 8 + xcd;
;     if (gp >= npatch) break;
;     ...
; #pragma unroll
;         for (int it = 0; it < 16; ++it) {
;           const int c = it * 64 + laneE, row = c >> 3, seg = c & 7;
;           const float4 v = *(const float4*)(et + row * 144 + seg * 16);
;           const size_t g = (row0 + row) * DM + col0 + j * 32 + seg * 4;
;           const float4 xv = *(const float4*)(p.x + g);
;           const float4 hv = make_float4(xv.x + v.x, xv.y + v.y, xv.z + v.z, xv.w + v.w);
;           *(float4*)(p.out + g) = hv;
;           uint2 hb; hb.x = pack2(hv.x, hv.y); hb.y = pack2(hv.z, hv.w);
;           *(uint2*)(p.xn + (row0 + row) * LDK + col0 + j * 32 + seg * 4) = hb;
;         }
	v_pk_add_f32 v[194:195], v[198:199], v[194:195]
	v_pk_add_f32 v[196:197], v[200:201], v[196:197]
	global_store_dwordx4 v[192:193], v[194:197], off sc1
	v_lshlrev_b64 v[198:199], 11, v[220:221]
	v_lshl_add_u64 v[198:199], v[198:199], 0, v[164:165]
	v_cvt_pk_bf16_f32 v194, v194, v195
	v_cvt_pk_bf16_f32 v195, v196, v197
	global_store_dwordx2 v[190:191], v[194:195], off
	global_load_dwordx4 v[202:205], v[186:187], off
	v_mad_u64_u32 v[196:197], s[12:13], v206, s14, v[166:167]
	ds_read_b128 v[206:209], v196
	v_mad_u64_u32 v[194:195], s[12:13], v210, s2, v[102:103]
	v_mad_i32_i24 v195, v211, s2, v195
	v_lshl_add_u64 v[194:195], v[194:195], 0, v[104:105]
	v_lshl_add_u64 v[200:201], s[20:21], 0, v[212:213]
	v_lshlrev_b64 v[222:223], 2, v[198:199]
	v_lshl_add_u64 v[198:199], v[194:195], 0, v[128:129]
	v_lshl_add_u64 v[194:195], s[52:53], 0, v[222:223]
	s_waitcnt vmcnt(0) lgkmcnt(0)
	v_pk_add_f32 v[202:203], v[206:207], v[202:203]
	v_pk_add_f32 v[204:205], v[208:209], v[204:205]
	global_store_dwordx4 v[200:201], v[202:205], off sc1
	v_lshlrev_b64 v[206:207], 11, v[242:243]
	v_lshl_add_u64 v[206:207], v[206:207], 0, v[164:165]
	v_cvt_pk_bf16_f32 v202, v202, v203
	v_cvt_pk_bf16_f32 v203, v204, v205
	global_store_dwordx2 v[198:199], v[202:203], off
	global_load_dwordx4 v[210:213], v[194:195], off
	v_mad_u64_u32 v[204:205], s[12:13], v214, s14, v[166:167]
	ds_read_b128 v[214:217], v204
	v_mad_u64_u32 v[202:203], s[12:13], v220, s2, v[102:103]
	v_mad_i32_i24 v203, v221, s2, v203
	v_lshl_add_u64 v[202:203], v[202:203], 0, v[104:105]
	v_lshl_add_u64 v[208:209], s[20:21], 0, v[222:223]
	v_lshlrev_b64 v[244:245], 2, v[206:207]
	v_lshl_add_u64 v[206:207], v[202:203], 0, v[128:129]
	v_lshl_add_u64 v[202:203], s[52:53], 0, v[244:245]
	s_waitcnt vmcnt(0) lgkmcnt(0)
	v_pk_add_f32 v[210:211], v[214:215], v[210:211]
	v_pk_add_f32 v[212:213], v[216:217], v[212:213]
	global_store_dwordx4 v[208:209], v[210:213], off sc1
	v_lshlrev_b64 v[214:215], 11, v[248:249]
	v_lshl_add_u64 v[214:215], v[214:215], 0, v[164:165]
	v_cvt_pk_bf16_f32 v210, v210, v211
	v_cvt_pk_bf16_f32 v211, v212, v213
	global_store_dwordx2 v[206:207], v[210:211], off
	global_load_dwordx4 v[220:223], v[202:203], off
	v_mad_u64_u32 v[212:213], s[12:13], v238, s14, v[166:167]
	ds_read_b128 v[238:241], v212
	v_mad_u64_u32 v[210:211], s[12:13], v242, s2, v[102:103]
	v_mad_i32_i24 v211, v243, s2, v211
	v_lshl_add_u64 v[210:211], v[210:211], 0, v[104:105]
	v_lshl_add_u64 v[216:217], s[20:21], 0, v[244:245]
	ds_read_b128 v[242:245], v218
	v_lshlrev_b64 v[250:251], 2, v[214:215]
	v_lshl_add_u64 v[214:215], v[210:211], 0, v[128:129]
	v_lshl_add_u64 v[210:211], s[52:53], 0, v[250:251]
	v_mad_u64_u32 v[102:103], s[12:13], v246, s2, v[102:103]
	v_mad_i32_i24 v103, v247, s2, v103
	v_lshl_add_u64 v[102:103], v[102:103], 0, v[104:105]
	v_lshl_add_u64 v[102:103], v[102:103], 0, v[128:129]
	s_waitcnt vmcnt(0) lgkmcnt(1)
	v_pk_add_f32 v[220:221], v[238:239], v[220:221]
	v_pk_add_f32 v[222:223], v[240:241], v[222:223]
	global_store_dwordx4 v[216:217], v[220:223], off sc1
	s_nop 1
	v_cvt_pk_bf16_f32 v220, v220, v221
	v_cvt_pk_bf16_f32 v221, v222, v223
	global_store_dwordx2 v[214:215], v[220:221], off
	global_load_dwordx4 v[238:241], v[210:211], off
	v_lshlrev_b64 v[220:221], 11, v[246:247]
	v_lshl_add_u64 v[164:165], v[220:221], 0, v[164:165]
	v_lshlrev_b64 v[248:249], 2, v[164:165]
	v_lshl_add_u64 v[222:223], s[20:21], 0, v[250:251]
	v_lshl_add_u64 v[220:221], v[162:163], 0, v[128:129]
	v_lshl_add_u64 v[164:165], s[52:53], 0, v[248:249]
	v_lshl_add_u64 v[104:105], s[20:21], 0, v[248:249]
	s_waitcnt vmcnt(0) lgkmcnt(0)
	v_pk_add_f32 v[238:239], v[242:243], v[238:239]
	v_pk_add_f32 v[240:241], v[244:245], v[240:241]
	v_cvt_pk_bf16_f32 v162, v238, v239
	v_cvt_pk_bf16_f32 v163, v240, v241
	global_store_dwordx4 v[222:223], v[238:241], off sc1
	global_store_dwordx2 v[220:221], v[162:163], off
	global_load_dwordx4 v[238:241], v[164:165], off
	v_mad_u64_u32 v[162:163], s[12:13], v148, s14, v[166:167]
	ds_read_b128 v[242:245], v162
	v_readlane_b32 s12, v254, 28
	s_add_i32 s16, s16, s12
	s_ashr_i32 s12, s16, 31
	s_lshr_b32 s12, s12, 27
	s_add_i32 s12, s16, s12
	s_ashr_i32 s12, s12, 5
	s_lshl_b32 s12, s12, 3
	v_readlane_b32 s13, v254, 24
	s_or_b32 s17, s12, s13
	s_cmp_gt_i32 s17, 31
	s_waitcnt vmcnt(0) lgkmcnt(0)
; __device__ __forceinline__ int accrow(int reg, int lh) { return (reg & 3) + 8 * (reg >> 2) + 4 * lh; }
; template <int EPI, int PN>
; __device__ void gemm_phase(const Params& p, const u16* __restrict__ A, const u16* __restrict__ Bt, int nNt, char* smem) {
;     ...
; #pragma unroll
;       for (int j = 0; j < 2; ++j) {
; #pragma unroll
;         for (int i = 0; i < 4; ++i)
; #pragma unroll
;           for (int r = 0; r < 16; ++r) *(float*)(et + (i * 32 + accrow(r, lhE)) * 144 + lrE * 4) = acc[i][j][r];
; #pragma unroll
;         for (int it = 0; it < 16; ++it) {
;           const int c = it * 64 + laneE, row = c >> 3, seg = c & 7;
;           const float4 v = *(const float4*)(et + row * 144 + seg * 16);
;           const size_t g = (row0 + row) * DM + col0 + j * 32 + seg * 4;
;           const float4 xv = *(const float4*)(p.x + g);
;           const float4 hv = make_float4(xv.x + v.x, xv.y + v.y, xv.z + v.z, xv.w + v.w);
;           *(float4*)(p.out + g) = hv;
;           uint2 hb; hb.x = pack2(hv.x, hv.y); hb.y = pack2(hv.z, hv.w);
;           *(uint2*)(p.xn + (row0 + row) * LDK + col0 + j * 32 + seg * 4) = hb;
;         }
	v_pk_add_f32 v[238:239], v[242:243], v[238:239]
	v_pk_add_f32 v[240:241], v[244:245], v[240:241]
	v_cvt_pk_bf16_f32 v148, v238, v239
	v_cvt_pk_bf16_f32 v149, v240, v241
	global_store_dwordx4 v[104:105], v[238:241], off sc1
	global_store_dwordx2 v[102:103], v[148:149], off
	global_load_dwordx4 v[238:241], v[160:161], off offset:128
	ds_write_b32 v159, v48
	ds_write_b32 v159, v49 offset:144
	ds_write_b32 v159, v50 offset:288
	ds_write_b32 v159, v51 offset:432
	ds_write_b32 v159, v52 offset:1152
	ds_write_b32 v159, v53 offset:1296
	ds_write_b32 v159, v54 offset:1440
	ds_write_b32 v159, v55 offset:1584
	ds_write_b32 v159, v56 offset:2304
	ds_write_b32 v159, v57 offset:2448
	ds_write_b32 v159, v58 offset:2592
	ds_write_b32 v159, v59 offset:2736
	ds_write_b32 v159, v60 offset:3456
	ds_write_b32 v159, v61 offset:3600
	ds_write_b32 v159, v62 offset:3744
	ds_write_b32 v159, v63 offset:3888
	ds_write_b32 v159, v32 offset:4608
	ds_write_b32 v159, v33 offset:4752
	ds_write_b32 v159, v34 offset:4896
	ds_write_b32 v159, v35 offset:5040
	ds_write_b32 v159, v36 offset:5760
	ds_write_b32 v159, v37 offset:5904
	ds_write_b32 v159, v38 offset:6048
	ds_write_b32 v159, v39 offset:6192
	ds_write_b32 v159, v40 offset:6912
	ds_write_b32 v159, v41 offset:7056
	ds_write_b32 v159, v42 offset:7200
	ds_write_b32 v159, v43 offset:7344
	ds_write_b32 v159, v44 offset:8064
	ds_write_b32 v159, v45 offset:8208
	ds_write_b32 v159, v46 offset:8352
	ds_write_b32 v159, v47 offset:8496
	ds_write_b32 v159, v16 offset:9216
	ds_write_b32 v159, v17 offset:9360
	ds_write_b32 v159, v18 offset:9504
	ds_write_b32 v159, v19 offset:9648
	ds_write_b32 v159, v20 offset:10368
	ds_write_b32 v159, v21 offset:10512
	ds_write_b32 v159, v22 offset:10656
	ds_write_b32 v159, v23 offset:10800
	ds_write_b32 v159, v24 offset:11520
	ds_write_b32 v159, v25 offset:11664
	ds_write_b32 v159, v26 offset:11808
	ds_write_b32 v159, v27 offset:11952
	ds_write_b32 v159, v28 offset:12672
	ds_write_b32 v159, v29 offset:12816
	ds_write_b32 v159, v30 offset:12960
	ds_write_b32 v159, v31 offset:13104
	ds_write_b32 v159, v0 offset:13824
	ds_write_b32 v159, v1 offset:13968
	ds_write_b32 v159, v2 offset:14112
	ds_write_b32 v159, v3 offset:14256
	ds_write_b32 v159, v4 offset:14976
	ds_write_b32 v159, v5 offset:15120
	ds_write_b32 v159, v6 offset:15264
	ds_write_b32 v159, v7 offset:15408
	ds_write_b32 v159, v8 offset:16128
	ds_write_b32 v159, v9 offset:16272
	ds_write_b32 v159, v10 offset:16416
	ds_write_b32 v159, v11 offset:16560
	ds_write_b32 v159, v12 offset:17280
	ds_write_b32 v159, v13 offset:17424
	ds_write_b32 v159, v14 offset:17568
	ds_write_b32 v159, v15 offset:17712
	ds_read_b128 v[0:3], v158
	ds_read_b128 v[4:7], v72
	s_waitcnt vmcnt(0) lgkmcnt(1)
	v_pk_add_f32 v[0:1], v[0:1], v[238:239]
	v_pk_add_f32 v[2:3], v[2:3], v[240:241]
	global_store_dwordx4 v[64:65], v[0:3], off offset:128 sc1
	s_nop 1
	v_cvt_pk_bf16_f32 v0, v0, v1
	v_cvt_pk_bf16_f32 v1, v2, v3
	global_store_dwordx2 v[66:67], v[0:1], off offset:64
	global_load_dwordx4 v[0:3], v[68:69], off offset:128
	s_waitcnt vmcnt(0) lgkmcnt(0)
	v_pk_add_f32 v[0:1], v[4:5], v[0:1]
	v_pk_add_f32 v[2:3], v[6:7], v[2:3]
	global_store_dwordx4 v[76:77], v[0:3], off offset:128 sc1
	ds_read_b128 v[4:7], v80
	s_nop 0
	v_cvt_pk_bf16_f32 v0, v0, v1
	v_cvt_pk_bf16_f32 v1, v2, v3
	global_store_dwordx2 v[74:75], v[0:1], off offset:64
	global_load_dwordx4 v[0:3], v[70:71], off offset:128
	s_waitcnt vmcnt(0) lgkmcnt(0)
	v_pk_add_f32 v[0:1], v[4:5], v[0:1]
	v_pk_add_f32 v[2:3], v[6:7], v[2:3]
	global_store_dwordx4 v[84:85], v[0:3], off offset:128 sc1
	ds_read_b128 v[4:7], v88
	s_nop 0
	v_cvt_pk_bf16_f32 v0, v0, v1
	v_cvt_pk_bf16_f32 v1, v2, v3
	global_store_dwordx2 v[82:83], v[0:1], off offset:64
	global_load_dwordx4 v[0:3], v[78:79], off offset:128
	s_waitcnt vmcnt(0) lgkmcnt(0)
	v_pk_add_f32 v[0:1], v[4:5], v[0:1]
	v_pk_add_f32 v[2:3], v[6:7], v[2:3]
	global_store_dwordx4 v[92:93], v[0:3], off offset:128 sc1
	ds_read_b128 v[4:7], v96
	s_nop 0
	v_cvt_pk_bf16_f32 v0, v0, v1
	v_cvt_pk_bf16_f32 v1, v2, v3
	global_store_dwordx2 v[90:91], v[0:1], off offset:64
	global_load_dwordx4 v[0:3], v[86:87], off offset:128
	s_waitcnt vmcnt(0) lgkmcnt(0)
; template <int EPI, int PN>
; __device__ void gemm_phase(const Params& p, const u16* __restrict__ A, const u16* __restrict__ Bt, int nNt, char* smem) {
;     ...
; #pragma unroll
;         for (int it = 0; it < 16; ++it) {
;           const int c = it * 64 + laneE, row = c >> 3, seg = c & 7;
;           const float4 v = *(const float4*)(et + row * 144 + seg * 16);
;           const size_t g = (row0 + row) * DM + col0 + j * 32 + seg * 4;
;           const float4 xv = *(const float4*)(p.x + g);
;           const float4 hv = make_float4(xv.x + v.x, xv.y + v.y, xv.z + v.z, xv.w + v.w);
;           *(float4*)(p.out + g) = hv;
;           uint2 hb; hb.x = pack2(hv.x, hv.y); hb.y = pack2(hv.z, hv.w);
;           *(uint2*)(p.xn + (row0 + row) * LDK + col0 + j * 32 + seg * 4) = hb;
;         }
	v_pk_add_f32 v[0:1], v[4:5], v[0:1]
	v_pk_add_f32 v[2:3], v[6:7], v[2:3]
	global_store_dwordx4 v[100:101], v[0:3], off offset:128 sc1
	ds_read_b128 v[4:7], v108
	s_nop 0
	v_cvt_pk_bf16_f32 v0, v0, v1
	v_cvt_pk_bf16_f32 v1, v2, v3
	global_store_dwordx2 v[98:99], v[0:1], off offset:64
	global_load_dwordx4 v[0:3], v[94:95], off offset:128
	s_waitcnt vmcnt(0) lgkmcnt(0)
	v_pk_add_f32 v[0:1], v[4:5], v[0:1]
	v_pk_add_f32 v[2:3], v[6:7], v[2:3]
	global_store_dwordx4 v[112:113], v[0:3], off offset:128 sc1
	ds_read_b128 v[4:7], v116
	s_nop 0
	v_cvt_pk_bf16_f32 v0, v0, v1
	v_cvt_pk_bf16_f32 v1, v2, v3
	global_store_dwordx2 v[110:111], v[0:1], off offset:64
	global_load_dwordx4 v[0:3], v[106:107], off offset:128
	s_waitcnt vmcnt(0) lgkmcnt(0)
	v_pk_add_f32 v[0:1], v[4:5], v[0:1]
	v_pk_add_f32 v[2:3], v[6:7], v[2:3]
	global_store_dwordx4 v[120:121], v[0:3], off offset:128 sc1
	ds_read_b128 v[4:7], v124
	s_nop 0
	v_cvt_pk_bf16_f32 v0, v0, v1
	v_cvt_pk_bf16_f32 v1, v2, v3
	global_store_dwordx2 v[118:119], v[0:1], off offset:64
	global_load_dwordx4 v[0:3], v[114:115], off offset:128
	s_waitcnt vmcnt(0) lgkmcnt(0)
	v_pk_add_f32 v[0:1], v[4:5], v[0:1]
	v_pk_add_f32 v[2:3], v[6:7], v[2:3]
	global_store_dwordx4 v[168:169], v[0:3], off offset:128 sc1
	ds_read_b128 v[4:7], v172
	s_nop 0
	v_cvt_pk_bf16_f32 v0, v0, v1
	v_cvt_pk_bf16_f32 v1, v2, v3
	global_store_dwordx2 v[126:127], v[0:1], off offset:64
	global_load_dwordx4 v[0:3], v[122:123], off offset:128
	s_waitcnt vmcnt(0) lgkmcnt(0)
	v_pk_add_f32 v[0:1], v[4:5], v[0:1]
	v_pk_add_f32 v[2:3], v[6:7], v[2:3]
	global_store_dwordx4 v[176:177], v[0:3], off offset:128 sc1
	ds_read_b128 v[4:7], v180
	s_nop 0
	v_cvt_pk_bf16_f32 v0, v0, v1
	v_cvt_pk_bf16_f32 v1, v2, v3
	global_store_dwordx2 v[174:175], v[0:1], off offset:64
	global_load_dwordx4 v[0:3], v[170:171], off offset:128
	s_waitcnt vmcnt(0) lgkmcnt(0)
	v_pk_add_f32 v[0:1], v[4:5], v[0:1]
	v_pk_add_f32 v[2:3], v[6:7], v[2:3]
	global_store_dwordx4 v[184:185], v[0:3], off offset:128 sc1
	ds_read_b128 v[4:7], v188
	s_nop 0
	v_cvt_pk_bf16_f32 v0, v0, v1
	v_cvt_pk_bf16_f32 v1, v2, v3
	global_store_dwordx2 v[182:183], v[0:1], off offset:64
	global_load_dwordx4 v[0:3], v[178:179], off offset:128
	s_waitcnt vmcnt(0) lgkmcnt(0)
	v_pk_add_f32 v[0:1], v[4:5], v[0:1]
	v_pk_add_f32 v[2:3], v[6:7], v[2:3]
	global_store_dwordx4 v[192:193], v[0:3], off offset:128 sc1
	ds_read_b128 v[4:7], v196
	s_nop 0
	v_cvt_pk_bf16_f32 v0, v0, v1
	v_cvt_pk_bf16_f32 v1, v2, v3
	global_store_dwordx2 v[190:191], v[0:1], off offset:64
	global_load_dwordx4 v[0:3], v[186:187], off offset:128
	s_waitcnt vmcnt(0) lgkmcnt(0)
	v_pk_add_f32 v[0:1], v[4:5], v[0:1]
	v_pk_add_f32 v[2:3], v[6:7], v[2:3]
	global_store_dwordx4 v[200:201], v[0:3], off offset:128 sc1
	ds_read_b128 v[4:7], v204
	s_nop 0
	v_cvt_pk_bf16_f32 v0, v0, v1
	v_cvt_pk_bf16_f32 v1, v2, v3
	global_store_dwordx2 v[198:199], v[0:1], off offset:64
	global_load_dwordx4 v[0:3], v[194:195], off offset:128
	s_waitcnt vmcnt(0) lgkmcnt(0)
	v_pk_add_f32 v[0:1], v[4:5], v[0:1]
	v_pk_add_f32 v[2:3], v[6:7], v[2:3]
	global_store_dwordx4 v[208:209], v[0:3], off offset:128 sc1
	ds_read_b128 v[4:7], v212
	s_nop 0
	v_cvt_pk_bf16_f32 v0, v0, v1
	v_cvt_pk_bf16_f32 v1, v2, v3
	global_store_dwordx2 v[206:207], v[0:1], off offset:64
	global_load_dwordx4 v[0:3], v[202:203], off offset:128
	s_waitcnt vmcnt(0) lgkmcnt(0)
	v_pk_add_f32 v[0:1], v[4:5], v[0:1]
	v_pk_add_f32 v[2:3], v[6:7], v[2:3]
	global_store_dwordx4 v[216:217], v[0:3], off offset:128 sc1
	ds_read_b128 v[4:7], v218
	s_nop 0
	v_cvt_pk_bf16_f32 v0, v0, v1
	v_cvt_pk_bf16_f32 v1, v2, v3
	global_store_dwordx2 v[214:215], v[0:1], off offset:64
	global_load_dwordx4 v[0:3], v[210:211], off offset:128
	s_waitcnt vmcnt(0) lgkmcnt(0)
	v_pk_add_f32 v[0:1], v[4:5], v[0:1]
	v_pk_add_f32 v[2:3], v[6:7], v[2:3]
	global_store_dwordx4 v[222:223], v[0:3], off offset:128 sc1
	ds_read_b128 v[4:7], v162
	s_nop 0
	v_cvt_pk_bf16_f32 v0, v0, v1
	v_cvt_pk_bf16_f32 v1, v2, v3
	global_store_dwordx2 v[220:221], v[0:1], off offset:64
	global_load_dwordx4 v[0:3], v[164:165], off offset:128
	s_waitcnt vmcnt(0) lgkmcnt(0)
	v_pk_add_f32 v[0:1], v[4:5], v[0:1]
	v_pk_add_f32 v[2:3], v[6:7], v[2:3]
	global_store_dwordx4 v[104:105], v[0:3], off offset:128 sc1
	s_nop 1
	v_cvt_pk_bf16_f32 v0, v0, v1
	v_cvt_pk_bf16_f32 v1, v2, v3
	global_store_dwordx2 v[102:103], v[0:1], off offset:64
	s_barrier
	s_cbranch_scc0 .LBB0_665

; template <int EPI, int PN>
; __device__ void gemm_phase(const Params& p, const u16* __restrict__ A, const u16* __restrict__ Bt, int nNt, char* smem) {
;     ...
;     for (int kt = 0; kt < 32; ++kt) {
;       asm volatile("s_waitcnt vmcnt(0)" ::: "memory");
;       __builtin_amdgcn_s_barrier();
;       const u16* Ab = ring + (kt & 1) * STG;
;       const u16* Bb = Ab + 16384;
;       u16* st = ring + ((kt + 1) & 1) * STG;
;       const bool pre = (kt + 1 < 32);
;       s16x8 af[2][4], bf[2][2];
;       auto ldfrag = [&](int ks, int slot) {
; #pragma unroll
;         for (int i = 0; i < 4; ++i) {
;           const int row = wr * 128 + i * 32 + lr;
;           af[slot][i] = *(const s16x8*)(Ab + row * 64 + (((ks * 2 + lh) ^ ((row >> 1) & 7)) * 8));
;         }
; #pragma unroll
;         for (int j = 0; j < 2; ++j) {
;           const int rowb = nh * 128 + wc * 64 + j * 32 + lr;
;           bf[slot][j] = *(const s16x8*)(Bb + rowb * 64 + (((ks * 2 + lh) ^ ((rowb >> 1) & 7)) * 8));
;         }
;       };
;       ldfrag(0, 0);
;       ldfrag(1, 1);
;       __builtin_amdgcn_sched_barrier(0);
; #pragma unroll
;       for (int ks = 0; ks < 4; ++ks) {
;         const int slot = ks & 1;
; #pragma unroll
;         for (int i = 0; i < 4; ++i) {
;           acc[i][0] = mfma32(af[slot][i], bf[slot][0], acc[i][0]);
;           acc[i][1] = mfma32(af[slot][i], bf[slot][1], acc[i][1]);
;           __builtin_amdgcn_sched_barrier(0);
;           if (pre && (i & 1) == 0) {
;             const int pi = ks * 2 + (i >> 1);
;             if (pi < 4) glds16(Ag0 + (size_t)pi * 64 * LDK + (kt + 1) * 64, st + (srow + 64 * pi) * 64 + sch * 8);
;             else glds16(Bg0 + (size_t)(pi - 4) * 64 * LDK + (kt + 1) * 64, st + 16384 + (srow + 64 * (pi - 4)) * 64 + sch * 8);
;             __builtin_amdgcn_sched_barrier(0);
;           }
;         }
;         if (ks + 2 < 4) { ldfrag(ks + 2, slot); __builtin_amdgcn_sched_barrier(0); }
;       }
.Lrot723_loop:
	s_add_i32 s15, s11, 0xffff8000
	s_and_b32 s15, s15, 0x8000
	s_lshl_b32 s15, s15, 1
	v_lshl_or_b32 v128, v143, 1, s15
	v_lshl_add_u32 v149, v147, 1, s15
	s_and_b32 s98, s11, 0x8000
	s_lshl_b32 s98, s98, 1
	s_waitcnt lgkmcnt(7)
	v_mfma_f32_32x32x16_bf16 v[112:127], v[178:181], v[194:197], v[112:127]
	v_add3_u32 v226, s98, v162, v156
	s_waitcnt lgkmcnt(6)
	v_mfma_f32_32x32x16_bf16 v[96:111], v[178:181], v[198:201], v[96:111]
	v_readfirstlane_b32 s100, v226
	s_mov_b32 s16, m0
	s_add_i32 m0, s100, 0x8000
	s_nop 0
	global_load_lds_dwordx4 v[160:161], off
	v_mfma_f32_32x32x16_bf16 v[80:95], v[182:185], v[194:197], v[80:95]
	v_lshl_add_u64 v[178:179], v[160:161], 0, s[2:3]
	s_add_i32 m0, s100, 0xa000
	s_nop 0
	global_load_lds_dwordx4 v[178:179], off
	v_mfma_f32_32x32x16_bf16 v[64:79], v[182:185], v[198:201], v[64:79]
	v_lshl_add_u64 v[180:181], v[160:161], 0, s[4:5]
	s_add_i32 m0, s100, 0xc000
	s_nop 0
	global_load_lds_dwordx4 v[180:181], off
	v_mfma_f32_32x32x16_bf16 v[48:63], v[186:189], v[194:197], v[48:63]
	v_lshl_add_u64 v[178:179], v[160:161], 0, s[6:7]
	s_add_i32 m0, s100, 0xe000
	s_nop 0
	global_load_lds_dwordx4 v[178:179], off
	s_mov_b32 m0, s16
	v_mfma_f32_32x32x16_bf16 v[32:47], v[186:189], v[198:201], v[32:47]
	v_mfma_f32_32x32x16_bf16 v[16:31], v[190:193], v[194:197], v[16:31]
	v_mfma_f32_32x32x16_bf16 v[0:15], v[190:193], v[198:201], v[0:15]
	v_lshl_add_u64 v[160:161], v[160:161], 0, s[8:9]
	v_add_u32_e32 v177, v128, v175
	ds_read_b128 v[178:181], v177
	ds_read_b128 v[182:185], v177 offset:4096
	ds_read_b128 v[186:189], v177 offset:8192
	ds_read_b128 v[190:193], v177 offset:12288
	v_add_u32_e32 v177, v149, v175
	ds_read_b128 v[194:197], v177 offset:32768
	ds_read_b128 v[198:201], v177 offset:36864
	s_waitcnt lgkmcnt(7)
	v_mfma_f32_32x32x16_bf16 v[112:127], v[202:205], v[218:221], v[112:127]
	s_waitcnt lgkmcnt(6)
	v_mfma_f32_32x32x16_bf16 v[96:111], v[202:205], v[222:225], v[96:111]
	v_mfma_f32_32x32x16_bf16 v[80:95], v[206:209], v[218:221], v[80:95]
	v_mfma_f32_32x32x16_bf16 v[64:79], v[206:209], v[222:225], v[64:79]
	v_mfma_f32_32x32x16_bf16 v[48:63], v[210:213], v[218:221], v[48:63]
	v_mfma_f32_32x32x16_bf16 v[32:47], v[210:213], v[222:225], v[32:47]
	v_mfma_f32_32x32x16_bf16 v[16:31], v[214:217], v[218:221], v[16:31]
	v_mfma_f32_32x32x16_bf16 v[0:15], v[214:217], v[222:225], v[0:15]
	v_add_u32_e32 v128, v128, v176
	ds_read_b128 v[202:205], v128
	ds_read_b128 v[206:209], v128 offset:4096
	ds_read_b128 v[210:213], v128 offset:8192
	ds_read_b128 v[214:217], v128 offset:12288
	v_add_u32_e32 v128, v149, v176
	ds_read_b128 v[218:221], v128 offset:32768
	ds_read_b128 v[222:225], v128 offset:36864
	s_waitcnt lgkmcnt(7)
	v_mfma_f32_32x32x16_bf16 v[112:127], v[178:181], v[194:197], v[112:127]
	s_waitcnt lgkmcnt(6)
	v_mfma_f32_32x32x16_bf16 v[96:111], v[178:181], v[198:201], v[96:111]
	v_mfma_f32_32x32x16_bf16 v[80:95], v[182:185], v[194:197], v[80:95]
	v_mfma_f32_32x32x16_bf16 v[64:79], v[182:185], v[198:201], v[64:79]
	v_mfma_f32_32x32x16_bf16 v[48:63], v[186:189], v[194:197], v[48:63]
	v_mfma_f32_32x32x16_bf16 v[32:47], v[186:189], v[198:201], v[32:47]
	v_mfma_f32_32x32x16_bf16 v[16:31], v[190:193], v[194:197], v[16:31]
	v_mfma_f32_32x32x16_bf16 v[0:15], v[190:193], v[198:201], v[0:15]
	v_lshl_or_b32 v227, v143, 1, s98
	v_lshl_add_u32 v229, v147, 1, s98
	v_add_u32_e32 v228, v227, v173
	v_add_u32_e32 v230, v229, v173
	s_waitcnt vmcnt(0) lgkmcnt(0)
	s_barrier
	ds_read_b128 v[178:181], v228
	ds_read_b128 v[182:185], v228 offset:4096
	ds_read_b128 v[186:189], v228 offset:8192
	ds_read_b128 v[190:193], v228 offset:12288
	ds_read_b128 v[194:197], v230 offset:32768
	ds_read_b128 v[198:201], v230 offset:36864
	v_add3_u32 v226, s15, v162, v156
	v_mfma_f32_32x32x16_bf16 v[112:127], v[202:205], v[218:221], v[112:127]
	v_readfirstlane_b32 s99, v226
	s_mov_b32 s16, m0
	s_mov_b32 m0, s99
	s_nop 0
	global_load_lds_dwordx4 v[158:159], off
	v_mfma_f32_32x32x16_bf16 v[96:111], v[202:205], v[222:225], v[96:111]
	v_lshl_add_u64 v[232:233], v[158:159], 0, s[2:3]
	s_add_i32 m0, s99, 0x2000
	s_nop 0
	global_load_lds_dwordx4 v[232:233], off
	v_mfma_f32_32x32x16_bf16 v[80:95], v[206:209], v[218:221], v[80:95]
	v_lshl_add_u64 v[234:235], v[158:159], 0, s[4:5]
	s_add_i32 m0, s99, 0x4000
	s_nop 0
	global_load_lds_dwordx4 v[234:235], off
	v_mfma_f32_32x32x16_bf16 v[64:79], v[206:209], v[222:225], v[64:79]
	v_lshl_add_u64 v[232:233], v[158:159], 0, s[6:7]
	s_add_i32 m0, s99, 0x6000
	s_nop 0
	global_load_lds_dwordx4 v[232:233], off
	s_mov_b32 m0, s16
	v_mfma_f32_32x32x16_bf16 v[48:63], v[210:213], v[218:221], v[48:63]
	v_mfma_f32_32x32x16_bf16 v[32:47], v[210:213], v[222:225], v[32:47]
	v_mfma_f32_32x32x16_bf16 v[16:31], v[214:217], v[218:221], v[16:31]
	v_mfma_f32_32x32x16_bf16 v[0:15], v[214:217], v[222:225], v[0:15]
	v_add_u32_e32 v228, v227, v174
	v_add_u32_e32 v230, v229, v174
	ds_read_b128 v[202:205], v228
	ds_read_b128 v[206:209], v228 offset:4096
	ds_read_b128 v[210:213], v228 offset:8192
	ds_read_b128 v[214:217], v228 offset:12288
	ds_read_b128 v[218:221], v230 offset:32768
	ds_read_b128 v[222:225], v230 offset:36864
	s_add_i32 s11, s11, 0x8000
	v_lshl_add_u64 v[158:159], v[158:159], 0, s[8:9]
	s_cmp_eq_u32 s11, 0xf8000
	s_cbranch_scc0 .Lrot723_loop
; template <int EPI, int PN>
; __device__ void gemm_phase(const Params& p, const u16* __restrict__ A, const u16* __restrict__ Bt, int nNt, char* smem) {
;     ...
;   for (int q = jb;; q += NJ) {
;     const int pl = q / (4 * PN), w = q % (4 * PN);
;     const int gp = pl * 8 + xcd;
;     if (gp >= npatch) break;
;     const int mt = (gp / npn) * 4 + (w & 3), nt = (gp % npn) * PN + (w >> 2);
;     const int gch = sch ^ ((srow >> 1) & 7);
;     const u16* Ag0 = A + (size_t)(mt * 256 + srow) * LDK + gch * 8;
;     const u16* Bg0 = Bt + (size_t)(nt * 256 + srow) * LDK + gch * 8;
;     ...
;     for (int kt = 0; kt < 32; ++kt) {
;       asm volatile("s_waitcnt vmcnt(0)" ::: "memory");
;       __builtin_amdgcn_s_barrier();
;       const u16* Ab = ring + (kt & 1) * STG;
;       const u16* Bb = Ab + 16384;
;       u16* st = ring + ((kt + 1) & 1) * STG;
;       const bool pre = (kt + 1 < 32);
;       s16x8 af[2][4], bf[2][2];
;       auto ldfrag = [&](int ks, int slot) {
; #pragma unroll
;         for (int i = 0; i < 4; ++i) {
;           const int row = wr * 128 + i * 32 + lr;
;           af[slot][i] = *(const s16x8*)(Ab + row * 64 + (((ks * 2 + lh) ^ ((row >> 1) & 7)) * 8));
;         }
; #pragma unroll
;         for (int j = 0; j < 2; ++j) {
;           const int rowb = nh * 128 + wc * 64 + j * 32 + lr;
;           bf[slot][j] = *(const s16x8*)(Bb + rowb * 64 + (((ks * 2 + lh) ^ ((rowb >> 1) & 7)) * 8));
;         }
;       };
;       ldfrag(0, 0);
;       ldfrag(1, 1);
;       __builtin_amdgcn_sched_barrier(0);
; #pragma unroll
;       for (int ks = 0; ks < 4; ++ks) {
;         const int slot = ks & 1;
; #pragma unroll
;         for (int i = 0; i < 4; ++i) {
;           acc[i][0] = mfma32(af[slot][i], bf[slot][0], acc[i][0]);
;           acc[i][1] = mfma32(af[slot][i], bf[slot][1], acc[i][1]);
;           __builtin_amdgcn_sched_barrier(0);
;           if (pre && (i & 1) == 0) {
;             const int pi = ks * 2 + (i >> 1);
;             if (pi < 4) glds16(Ag0 + (size_t)pi * 64 * LDK + (kt + 1) * 64, st + (srow + 64 * pi) * 64 + sch * 8);
;             else glds16(Bg0 + (size_t)(pi - 4) * 64 * LDK + (kt + 1) * 64, st + 16384 + (srow + 64 * (pi - 4)) * 64 + sch * 8);
;             __builtin_amdgcn_sched_barrier(0);
;           }
;         }
;         if (ks + 2 < 4) { ldfrag(ks + 2, slot); __builtin_amdgcn_sched_barrier(0); }
;       }
	s_add_i32 s15, s11, 0xffff8000
	s_and_b32 s15, s15, 0x8000
	s_lshl_b32 s15, s15, 1
	v_lshl_or_b32 v128, v143, 1, s15
	v_lshl_add_u32 v149, v147, 1, s15
	s_and_b32 s98, s11, 0x8000
	s_lshl_b32 s98, s98, 1
	s_waitcnt lgkmcnt(7)
	v_mfma_f32_32x32x16_bf16 v[112:127], v[178:181], v[194:197], v[112:127]
	v_add3_u32 v226, s98, v162, v156
	s_waitcnt lgkmcnt(6)
	v_mfma_f32_32x32x16_bf16 v[96:111], v[178:181], v[198:201], v[96:111]
	v_readfirstlane_b32 s100, v226
	s_mov_b32 s16, m0
	s_add_i32 m0, s100, 0x8000
	s_nop 0
	global_load_lds_dwordx4 v[160:161], off
	v_mfma_f32_32x32x16_bf16 v[80:95], v[182:185], v[194:197], v[80:95]
	v_lshl_add_u64 v[178:179], v[160:161], 0, s[2:3]
	s_add_i32 m0, s100, 0xa000
	s_nop 0
	global_load_lds_dwordx4 v[178:179], off
	v_mfma_f32_32x32x16_bf16 v[64:79], v[182:185], v[198:201], v[64:79]
	v_lshl_add_u64 v[180:181], v[160:161], 0, s[4:5]
	s_add_i32 m0, s100, 0xc000
	s_nop 0
	global_load_lds_dwordx4 v[180:181], off
	v_mfma_f32_32x32x16_bf16 v[48:63], v[186:189], v[194:197], v[48:63]
	v_lshl_add_u64 v[178:179], v[160:161], 0, s[6:7]
	s_add_i32 m0, s100, 0xe000
	s_nop 0
	global_load_lds_dwordx4 v[178:179], off
	s_mov_b32 m0, s16
	v_mfma_f32_32x32x16_bf16 v[32:47], v[186:189], v[198:201], v[32:47]
	v_mfma_f32_32x32x16_bf16 v[16:31], v[190:193], v[194:197], v[16:31]
	v_mfma_f32_32x32x16_bf16 v[0:15], v[190:193], v[198:201], v[0:15]
	v_lshl_add_u64 v[160:161], v[160:161], 0, s[8:9]
	v_add_u32_e32 v177, v128, v175
	ds_read_b128 v[178:181], v177
	ds_read_b128 v[182:185], v177 offset:4096
	ds_read_b128 v[186:189], v177 offset:8192
	ds_read_b128 v[190:193], v177 offset:12288
	v_add_u32_e32 v177, v149, v175
	ds_read_b128 v[194:197], v177 offset:32768
	ds_read_b128 v[198:201], v177 offset:36864
	s_waitcnt lgkmcnt(7)
	v_mfma_f32_32x32x16_bf16 v[112:127], v[202:205], v[218:221], v[112:127]
	s_waitcnt lgkmcnt(6)
	v_mfma_f32_32x32x16_bf16 v[96:111], v[202:205], v[222:225], v[96:111]
	v_mfma_f32_32x32x16_bf16 v[80:95], v[206:209], v[218:221], v[80:95]
	v_mfma_f32_32x32x16_bf16 v[64:79], v[206:209], v[222:225], v[64:79]
	v_mfma_f32_32x32x16_bf16 v[48:63], v[210:213], v[218:221], v[48:63]
	v_mfma_f32_32x32x16_bf16 v[32:47], v[210:213], v[222:225], v[32:47]
	v_mfma_f32_32x32x16_bf16 v[16:31], v[214:217], v[218:221], v[16:31]
	v_mfma_f32_32x32x16_bf16 v[0:15], v[214:217], v[222:225], v[0:15]
	v_add_u32_e32 v128, v128, v176
	ds_read_b128 v[202:205], v128
	ds_read_b128 v[206:209], v128 offset:4096
	ds_read_b128 v[210:213], v128 offset:8192
	ds_read_b128 v[214:217], v128 offset:12288
	v_add_u32_e32 v128, v149, v176
	ds_read_b128 v[218:221], v128 offset:32768
	ds_read_b128 v[222:225], v128 offset:36864
	v_readlane_b32 s98, v254, 28
	v_readlane_b32 s99, v254, 24
	s_nop 1
	s_add_i32 s98, s34, s98
	s_lshr_b32 s100, s98, 5
	s_lshl_b32 s101, s100, 3
	s_or_b32 s101, s101, s99
	s_cmp_lt_i32 s101, 32
	s_cselect_b32 s98, s98, s34
	s_lshr_b32 s100, s98, 5
	s_and_b32 s101, s98, 31
	s_lshl_b32 s100, s100, 3
	s_or_b32 s100, s100, s99
	s_and_b32 s99, s101, 3
	s_lshl_b32 s100, s100, 2
	s_or_b32 s100, s100, s99
	s_ashr_i32 s101, s101, 2
	v_lshrrev_b32_e32 v236, 6, v252
	v_and_b32_e32 v237, 3, v236
	v_lshl_add_u32 v237, v237, 6, v135
	v_mov_b32_e32 v238, s101
	v_mov_b32_e32 v239, s100
	v_cmp_gt_u32_e32 vcc, 4, v236
	v_readlane_b32 s98, v253, 29
	v_readlane_b32 s99, v253, 30
	v_readlane_b32 s100, v253, 35
	v_readlane_b32 s101, v253, 36
	v_cndmask_b32_e32 v238, v238, v239, vcc
	v_lshl_add_u32 v237, v238, 8, v237
	v_mov_b32_e32 v240, s100
	v_mov_b32_e32 v241, s101
	v_mov_b32_e32 v242, s98
	v_mov_b32_e32 v243, s99
	v_cndmask_b32_e32 v240, v240, v242, vcc
	v_cndmask_b32_e32 v241, v241, v243, vcc
	v_mad_u64_u32 v[240:241], s[98:99], v237, s0, v[240:241]
	global_load_dword v236, v[240:241], off
	global_load_dword v237, v[240:241], off offset:128
	s_waitcnt lgkmcnt(7)
	v_mfma_f32_32x32x16_bf16 v[112:127], v[178:181], v[194:197], v[112:127]
	s_waitcnt lgkmcnt(6)
	v_mfma_f32_32x32x16_bf16 v[96:111], v[178:181], v[198:201], v[96:111]
	v_mfma_f32_32x32x16_bf16 v[80:95], v[182:185], v[194:197], v[80:95]
	v_mfma_f32_32x32x16_bf16 v[64:79], v[182:185], v[198:201], v[64:79]
	v_mfma_f32_32x32x16_bf16 v[48:63], v[186:189], v[194:197], v[48:63]
	v_mfma_f32_32x32x16_bf16 v[32:47], v[186:189], v[198:201], v[32:47]
	v_mfma_f32_32x32x16_bf16 v[16:31], v[190:193], v[194:197], v[16:31]
	v_mfma_f32_32x32x16_bf16 v[0:15], v[190:193], v[198:201], v[0:15]
	s_waitcnt lgkmcnt(1)
	v_mfma_f32_32x32x16_bf16 v[112:127], v[202:205], v[218:221], v[112:127]
	s_waitcnt lgkmcnt(0)
	v_mfma_f32_32x32x16_bf16 v[96:111], v[202:205], v[222:225], v[96:111]
	v_mfma_f32_32x32x16_bf16 v[80:95], v[206:209], v[218:221], v[80:95]
	v_mfma_f32_32x32x16_bf16 v[64:79], v[206:209], v[222:225], v[64:79]
	v_mfma_f32_32x32x16_bf16 v[48:63], v[210:213], v[218:221], v[48:63]
	v_mfma_f32_32x32x16_bf16 v[32:47], v[210:213], v[222:225], v[32:47]
	v_mfma_f32_32x32x16_bf16 v[16:31], v[214:217], v[218:221], v[16:31]
	v_mfma_f32_32x32x16_bf16 v[0:15], v[214:217], v[222:225], v[0:15]
	s_waitcnt vmcnt(2)
	s_barrier
; __device__ __forceinline__ int accrow(int reg, int lh) { return (reg & 3) + 8 * (reg >> 2) + 4 * lh; }
; template <int EPI, int PN>
; __device__ void gemm_phase(const Params& p, const u16* __restrict__ A, const u16* __restrict__ Bt, int nNt, char* smem) {
;     ...
;       for (int ks = 0; ks < 4; ++ks) {
;         const int slot = ks & 1;
; #pragma unroll
;         for (int i = 0; i < 4; ++i) {
;           acc[i][0] = mfma32(af[slot][i], bf[slot][0], acc[i][0]);
;           acc[i][1] = mfma32(af[slot][i], bf[slot][1], acc[i][1]);
;           __builtin_amdgcn_sched_barrier(0);
;           if (pre && (i & 1) == 0) {
;             const int pi = ks * 2 + (i >> 1);
;             if (pi < 4) glds16(Ag0 + (size_t)pi * 64 * LDK + (kt + 1) * 64, st + (srow + 64 * pi) * 64 + sch * 8);
;             else glds16(Bg0 + (size_t)(pi - 4) * 64 * LDK + (kt + 1) * 64, st + 16384 + (srow + 64 * (pi - 4)) * 64 + sch * 8);
;             __builtin_amdgcn_sched_barrier(0);
;           }
;         }
;         if (ks + 2 < 4) { ldfrag(ks + 2, slot); __builtin_amdgcn_sched_barrier(0); }
;       }
;     ...
; #pragma unroll
;       for (int i = 0; i < 4; ++i)
; #pragma unroll
;         for (int j = 0; j < 2; ++j)
; #pragma unroll
;           for (int r = 0; r < 16; ++r) *(u16*)(et + (i * 32 + accrow(r, lhE)) * 144 + (j * 32 + lrE) * 2) = f2bf(acc[i][j][r]);
	ds_read_b128 v[158:161], v164
	ds_read_b128 v[178:181], v164 offset:4096
	ds_read_b128 v[182:185], v164 offset:8192
	ds_read_b128 v[186:189], v164 offset:12288
	ds_read_b128 v[190:193], v165
	ds_read_b128 v[194:197], v165 offset:4096
	ds_read_b128 v[198:201], v166
	ds_read_b128 v[202:205], v166 offset:4096
	ds_read_b128 v[206:209], v166 offset:8192
	ds_read_b128 v[210:213], v166 offset:12288
	ds_read_b128 v[214:217], v168
	ds_read_b128 v[218:221], v168 offset:4096
	s_waitcnt lgkmcnt(7)
	v_mfma_f32_32x32x16_bf16 v[112:127], v[158:161], v[190:193], v[112:127]
	s_waitcnt lgkmcnt(6)
	v_mfma_f32_32x32x16_bf16 v[96:111], v[158:161], v[194:197], v[96:111]
	v_mfma_f32_32x32x16_bf16 v[80:95], v[178:181], v[190:193], v[80:95]
	v_mfma_f32_32x32x16_bf16 v[64:79], v[178:181], v[194:197], v[64:79]
	v_mfma_f32_32x32x16_bf16 v[48:63], v[182:185], v[190:193], v[48:63]
	v_mfma_f32_32x32x16_bf16 v[32:47], v[182:185], v[194:197], v[32:47]
	v_mfma_f32_32x32x16_bf16 v[16:31], v[186:189], v[190:193], v[16:31]
	v_mfma_f32_32x32x16_bf16 v[0:15], v[186:189], v[194:197], v[0:15]
	ds_read_b128 v[158:161], v169
	ds_read_b128 v[178:181], v169 offset:4096
	ds_read_b128 v[182:185], v169 offset:8192
	ds_read_b128 v[186:189], v169 offset:12288
	ds_read_b128 v[190:193], v170
	ds_read_b128 v[194:197], v170 offset:4096
	s_waitcnt lgkmcnt(7)
	v_mfma_f32_32x32x16_bf16 v[112:127], v[198:201], v[214:217], v[112:127]
	s_waitcnt lgkmcnt(6)
	v_mfma_f32_32x32x16_bf16 v[96:111], v[198:201], v[218:221], v[96:111]
	v_mfma_f32_32x32x16_bf16 v[80:95], v[202:205], v[214:217], v[80:95]
	v_mfma_f32_32x32x16_bf16 v[64:79], v[202:205], v[218:221], v[64:79]
	v_mfma_f32_32x32x16_bf16 v[48:63], v[206:209], v[214:217], v[48:63]
	v_mfma_f32_32x32x16_bf16 v[32:47], v[206:209], v[218:221], v[32:47]
	v_mfma_f32_32x32x16_bf16 v[16:31], v[210:213], v[214:217], v[16:31]
	v_mfma_f32_32x32x16_bf16 v[0:15], v[210:213], v[218:221], v[0:15]
	ds_read_b128 v[198:201], v171
	ds_read_b128 v[202:205], v171 offset:4096
	ds_read_b128 v[206:209], v171 offset:8192
	ds_read_b128 v[210:213], v171 offset:12288
	ds_read_b128 v[214:217], v172
	ds_read_b128 v[218:221], v172 offset:4096
	s_waitcnt lgkmcnt(7)
	v_mfma_f32_32x32x16_bf16 v[112:127], v[158:161], v[190:193], v[112:127]
	s_waitcnt lgkmcnt(6)
	v_mfma_f32_32x32x16_bf16 v[96:111], v[158:161], v[194:197], v[96:111]
	v_mfma_f32_32x32x16_bf16 v[80:95], v[178:181], v[190:193], v[80:95]
	v_mfma_f32_32x32x16_bf16 v[64:79], v[178:181], v[194:197], v[64:79]
	v_mfma_f32_32x32x16_bf16 v[48:63], v[182:185], v[190:193], v[48:63]
	v_mfma_f32_32x32x16_bf16 v[32:47], v[182:185], v[194:197], v[32:47]
	v_mfma_f32_32x32x16_bf16 v[16:31], v[186:189], v[190:193], v[16:31]
	v_mfma_f32_32x32x16_bf16 v[0:15], v[186:189], v[194:197], v[0:15]
	s_waitcnt lgkmcnt(1)
	v_mfma_f32_32x32x16_bf16 v[112:127], v[198:201], v[214:217], v[112:127]
	s_waitcnt lgkmcnt(0)
	v_mfma_f32_32x32x16_bf16 v[96:111], v[198:201], v[218:221], v[96:111]
	v_mfma_f32_32x32x16_bf16 v[80:95], v[202:205], v[214:217], v[80:95]
	v_mfma_f32_32x32x16_bf16 v[64:79], v[202:205], v[218:221], v[64:79]
	v_mfma_f32_32x32x16_bf16 v[48:63], v[206:209], v[214:217], v[48:63]
	v_mfma_f32_32x32x16_bf16 v[32:47], v[206:209], v[218:221], v[32:47]
	v_mfma_f32_32x32x16_bf16 v[16:31], v[210:213], v[214:217], v[16:31]
	v_mfma_f32_32x32x16_bf16 v[0:15], v[210:213], v[218:221], v[0:15]
	v_mov_b32_e32 v149, v135
	v_mov_b32_e32 v128, v139
	v_mov_b32_e32 v158, v137
	s_barrier
	s_nop 7
	v_cvt_pk_bf16_f32 v0, v0, s0
	v_lshlrev_b32_e32 v158, 1, v158
	v_mul_lo_u32 v128, v128, s12
	v_add3_u32 v128, v163, v158, v128
	v_cvt_pk_bf16_f32 v112, v112, s0
	v_cvt_pk_bf16_f32 v96, v96, s0
	v_cvt_pk_bf16_f32 v80, v80, s0
	v_cvt_pk_bf16_f32 v64, v64, s0
	v_cvt_pk_bf16_f32 v48, v48, s0
	v_cvt_pk_bf16_f32 v32, v32, s0
	v_cvt_pk_bf16_f32 v16, v16, s0
	ds_write_b16 v128, v0 offset:13888
	v_cvt_pk_bf16_f32 v0, v1, s0
	ds_write_b16 v128, v112
	v_cvt_pk_bf16_f32 v112, v113, s0
	ds_write_b16 v128, v96 offset:64
	v_cvt_pk_bf16_f32 v96, v97, s0
	ds_write_b16 v128, v80 offset:4608
	v_cvt_pk_bf16_f32 v80, v81, s0
	ds_write_b16 v128, v64 offset:4672
	v_cvt_pk_bf16_f32 v64, v65, s0
	ds_write_b16 v128, v48 offset:9216
	v_cvt_pk_bf16_f32 v48, v49, s0
	ds_write_b16 v128, v32 offset:9280
	v_cvt_pk_bf16_f32 v32, v33, s0
	ds_write_b16 v128, v16 offset:13824
	v_cvt_pk_bf16_f32 v16, v17, s0
	ds_write_b16 v128, v0 offset:14032
	v_cvt_pk_bf16_f32 v0, v2, s0
	ds_write_b16 v128, v112 offset:144
	v_cvt_pk_bf16_f32 v112, v114, s0
	ds_write_b16 v128, v96 offset:208
	v_cvt_pk_bf16_f32 v96, v98, s0
	ds_write_b16 v128, v80 offset:4752
	v_cvt_pk_bf16_f32 v80, v82, s0
	ds_write_b16 v128, v64 offset:4816
	v_cvt_pk_bf16_f32 v64, v66, s0
	ds_write_b16 v128, v48 offset:9360
	v_cvt_pk_bf16_f32 v48, v50, s0
	ds_write_b16 v128, v32 offset:9424
	v_cvt_pk_bf16_f32 v32, v34, s0
	ds_write_b16 v128, v16 offset:13968
	v_cvt_pk_bf16_f32 v16, v18, s0
	ds_write_b16 v128, v0 offset:14176
	v_cvt_pk_bf16_f32 v0, v3, s0
	ds_write_b16 v128, v112 offset:288
	v_cvt_pk_bf16_f32 v112, v115, s0
	ds_write_b16 v128, v96 offset:352
	v_cvt_pk_bf16_f32 v96, v99, s0
	ds_write_b16 v128, v80 offset:4896
	v_cvt_pk_bf16_f32 v80, v83, s0
	ds_write_b16 v128, v64 offset:4960
	v_cvt_pk_bf16_f32 v64, v67, s0
	ds_write_b16 v128, v48 offset:9504
	v_cvt_pk_bf16_f32 v48, v51, s0
	ds_write_b16 v128, v32 offset:9568
	v_cvt_pk_bf16_f32 v32, v35, s0
	ds_write_b16 v128, v16 offset:14112
	v_cvt_pk_bf16_f32 v16, v19, s0
	ds_write_b16 v128, v0 offset:14320
	v_cvt_pk_bf16_f32 v0, v4, s0
	ds_write_b16 v128, v112 offset:432
	v_cvt_pk_bf16_f32 v112, v116, s0
	ds_write_b16 v128, v96 offset:496
	v_cvt_pk_bf16_f32 v96, v100, s0
	ds_write_b16 v128, v80 offset:5040
; __device__ __forceinline__ int accrow(int reg, int lh) { return (reg & 3) + 8 * (reg >> 2) + 4 * lh; }
; template <int EPI, int PN>
; __device__ void gemm_phase(const Params& p, const u16* __restrict__ A, const u16* __restrict__ Bt, int nNt, char* smem) {
;     ...
; #pragma unroll
;       for (int i = 0; i < 4; ++i)
; #pragma unroll
;         for (int j = 0; j < 2; ++j)
; #pragma unroll
;           for (int r = 0; r < 16; ++r) *(u16*)(et + (i * 32 + accrow(r, lhE)) * 144 + (j * 32 + lrE) * 2) = f2bf(acc[i][j][r]);
	v_cvt_pk_bf16_f32 v80, v84, s0
	ds_write_b16 v128, v64 offset:5104
	v_cvt_pk_bf16_f32 v64, v68, s0
	ds_write_b16 v128, v48 offset:9648
	v_cvt_pk_bf16_f32 v48, v52, s0
	ds_write_b16 v128, v32 offset:9712
	v_cvt_pk_bf16_f32 v32, v36, s0
	ds_write_b16 v128, v16 offset:14256
	v_cvt_pk_bf16_f32 v16, v20, s0
	ds_write_b16 v128, v0 offset:15040
	v_cvt_pk_bf16_f32 v0, v5, s0
	ds_write_b16 v128, v112 offset:1152
	v_cvt_pk_bf16_f32 v112, v117, s0
	ds_write_b16 v128, v96 offset:1216
	v_cvt_pk_bf16_f32 v96, v101, s0
	ds_write_b16 v128, v80 offset:5760
	v_cvt_pk_bf16_f32 v80, v85, s0
	ds_write_b16 v128, v64 offset:5824
	v_cvt_pk_bf16_f32 v64, v69, s0
	ds_write_b16 v128, v48 offset:10368
	v_cvt_pk_bf16_f32 v48, v53, s0
	ds_write_b16 v128, v32 offset:10432
	v_cvt_pk_bf16_f32 v32, v37, s0
	ds_write_b16 v128, v16 offset:14976
	v_cvt_pk_bf16_f32 v16, v21, s0
	ds_write_b16 v128, v0 offset:15184
	v_cvt_pk_bf16_f32 v0, v6, s0
	ds_write_b16 v128, v112 offset:1296
	v_cvt_pk_bf16_f32 v112, v118, s0
	ds_write_b16 v128, v96 offset:1360
	v_cvt_pk_bf16_f32 v96, v102, s0
	ds_write_b16 v128, v80 offset:5904
	v_cvt_pk_bf16_f32 v80, v86, s0
	ds_write_b16 v128, v64 offset:5968
	v_cvt_pk_bf16_f32 v64, v70, s0
	ds_write_b16 v128, v48 offset:10512
	v_cvt_pk_bf16_f32 v48, v54, s0
	ds_write_b16 v128, v32 offset:10576
	v_cvt_pk_bf16_f32 v32, v38, s0
	ds_write_b16 v128, v16 offset:15120
	v_cvt_pk_bf16_f32 v16, v22, s0
	ds_write_b16 v128, v0 offset:15328
	v_cvt_pk_bf16_f32 v0, v7, s0
	ds_write_b16 v128, v112 offset:1440
	v_cvt_pk_bf16_f32 v112, v119, s0
	ds_write_b16 v128, v96 offset:1504
	v_cvt_pk_bf16_f32 v96, v103, s0
	ds_write_b16 v128, v80 offset:6048
	v_cvt_pk_bf16_f32 v80, v87, s0
	ds_write_b16 v128, v64 offset:6112
	v_cvt_pk_bf16_f32 v64, v71, s0
	ds_write_b16 v128, v48 offset:10656
	v_cvt_pk_bf16_f32 v48, v55, s0
	ds_write_b16 v128, v32 offset:10720
	v_cvt_pk_bf16_f32 v32, v39, s0
	ds_write_b16 v128, v16 offset:15264
	v_cvt_pk_bf16_f32 v16, v23, s0
	ds_write_b16 v128, v0 offset:15472
	v_cvt_pk_bf16_f32 v0, v8, s0
	ds_write_b16 v128, v112 offset:1584
	v_cvt_pk_bf16_f32 v112, v120, s0
	ds_write_b16 v128, v96 offset:1648
	v_cvt_pk_bf16_f32 v96, v104, s0
	ds_write_b16 v128, v80 offset:6192
	v_cvt_pk_bf16_f32 v80, v88, s0
	ds_write_b16 v128, v64 offset:6256
	v_cvt_pk_bf16_f32 v64, v72, s0
	ds_write_b16 v128, v48 offset:10800
	v_cvt_pk_bf16_f32 v48, v56, s0
	ds_write_b16 v128, v32 offset:10864
	v_cvt_pk_bf16_f32 v32, v40, s0
	ds_write_b16 v128, v16 offset:15408
	v_cvt_pk_bf16_f32 v16, v24, s0
	ds_write_b16 v128, v0 offset:16192
	v_cvt_pk_bf16_f32 v0, v9, s0
	ds_write_b16 v128, v112 offset:2304
	v_cvt_pk_bf16_f32 v112, v121, s0
	ds_write_b16 v128, v96 offset:2368
	v_cvt_pk_bf16_f32 v96, v105, s0
	ds_write_b16 v128, v80 offset:6912
	v_cvt_pk_bf16_f32 v80, v89, s0
	ds_write_b16 v128, v64 offset:6976
	v_cvt_pk_bf16_f32 v64, v73, s0
	ds_write_b16 v128, v48 offset:11520
	v_cvt_pk_bf16_f32 v48, v57, s0
	ds_write_b16 v128, v32 offset:11584
	v_cvt_pk_bf16_f32 v32, v41, s0
	ds_write_b16 v128, v16 offset:16128
	v_cvt_pk_bf16_f32 v16, v25, s0
	ds_write_b16 v128, v0 offset:16336
	v_cvt_pk_bf16_f32 v0, v10, s0
	ds_write_b16 v128, v112 offset:2448
	v_cvt_pk_bf16_f32 v112, v122, s0
	ds_write_b16 v128, v96 offset:2512
	v_cvt_pk_bf16_f32 v96, v106, s0
	ds_write_b16 v128, v80 offset:7056
	v_cvt_pk_bf16_f32 v80, v90, s0
	ds_write_b16 v128, v64 offset:7120
	v_cvt_pk_bf16_f32 v64, v74, s0
	ds_write_b16 v128, v48 offset:11664
	v_cvt_pk_bf16_f32 v48, v58, s0
	ds_write_b16 v128, v32 offset:11728
	v_cvt_pk_bf16_f32 v32, v42, s0
	ds_write_b16 v128, v16 offset:16272
	v_cvt_pk_bf16_f32 v16, v26, s0
	ds_write_b16 v128, v0 offset:16480
	v_cvt_pk_bf16_f32 v0, v11, s0
	ds_write_b16 v128, v112 offset:2592
	v_cvt_pk_bf16_f32 v112, v123, s0
	ds_write_b16 v128, v96 offset:2656
	v_cvt_pk_bf16_f32 v96, v107, s0
	ds_write_b16 v128, v80 offset:7200
	v_cvt_pk_bf16_f32 v80, v91, s0
	ds_write_b16 v128, v64 offset:7264
	v_cvt_pk_bf16_f32 v64, v75, s0
	ds_write_b16 v128, v48 offset:11808
	v_cvt_pk_bf16_f32 v48, v59, s0
	ds_write_b16 v128, v32 offset:11872
	v_cvt_pk_bf16_f32 v32, v43, s0
	ds_write_b16 v128, v16 offset:16416
	v_cvt_pk_bf16_f32 v16, v27, s0
	ds_write_b16 v128, v0 offset:16624
	v_cvt_pk_bf16_f32 v0, v12, s0
	ds_write_b16 v128, v112 offset:2736
	v_cvt_pk_bf16_f32 v112, v124, s0
	ds_write_b16 v128, v96 offset:2800
	v_cvt_pk_bf16_f32 v96, v108, s0
	ds_write_b16 v128, v80 offset:7344
	v_cvt_pk_bf16_f32 v80, v92, s0
	ds_write_b16 v128, v64 offset:7408
	v_cvt_pk_bf16_f32 v64, v76, s0
	ds_write_b16 v128, v48 offset:11952
	v_cvt_pk_bf16_f32 v48, v60, s0
	ds_write_b16 v128, v32 offset:12016
	v_cvt_pk_bf16_f32 v32, v44, s0
	ds_write_b16 v128, v16 offset:16560
	v_cvt_pk_bf16_f32 v16, v28, s0
	ds_write_b16 v128, v0 offset:17344
	v_cvt_pk_bf16_f32 v0, v13, s0
	ds_write_b16 v128, v112 offset:3456
	v_cvt_pk_bf16_f32 v112, v125, s0
	ds_write_b16 v128, v96 offset:3520
	v_cvt_pk_bf16_f32 v96, v109, s0
	ds_write_b16 v128, v80 offset:8064
	v_cvt_pk_bf16_f32 v80, v93, s0
	ds_write_b16 v128, v64 offset:8128
	v_cvt_pk_bf16_f32 v64, v77, s0
	ds_write_b16 v128, v48 offset:12672
	v_cvt_pk_bf16_f32 v48, v61, s0
	ds_write_b16 v128, v32 offset:12736
	v_cvt_pk_bf16_f32 v32, v45, s0
	ds_write_b16 v128, v16 offset:17280
	v_cvt_pk_bf16_f32 v16, v29, s0
	ds_write_b16 v128, v0 offset:17488
	v_cvt_pk_bf16_f32 v0, v14, s0
	ds_write_b16 v128, v112 offset:3600
	v_cvt_pk_bf16_f32 v112, v126, s0
	ds_write_b16 v128, v96 offset:3664
	v_cvt_pk_bf16_f32 v96, v110, s0
	ds_write_b16 v128, v80 offset:8208
	v_cvt_pk_bf16_f32 v80, v94, s0
	ds_write_b16 v128, v64 offset:8272
	v_cvt_pk_bf16_f32 v64, v78, s0
	ds_write_b16 v128, v48 offset:12816
; __device__ __forceinline__ int accrow(int reg, int lh) { return (reg & 3) + 8 * (reg >> 2) + 4 * lh; }
; template <int EPI, int PN>
; __device__ void gemm_phase(const Params& p, const u16* __restrict__ A, const u16* __restrict__ Bt, int nNt, char* smem) {
;     ...
; #pragma unroll
;       for (int i = 0; i < 4; ++i)
; #pragma unroll
;         for (int j = 0; j < 2; ++j)
; #pragma unroll
;           for (int r = 0; r < 16; ++r) *(u16*)(et + (i * 32 + accrow(r, lhE)) * 144 + (j * 32 + lrE) * 2) = f2bf(acc[i][j][r]);
; #pragma unroll
;       for (int it = 0; it < 16; ++it) {
;         const int c = it * 64 + laneE, row = c >> 3, seg = c & 7;
;         const uint4 v = *(const uint4*)(et + row * 144 + seg * 16);
;         if (EPI == 0) *(uint4*)(p.proj + (row0 + row) * NPROJ + col0 + seg * 8) = v;
;         else *(uint4*)(p.qp + (row0 + row) * DM + col0 + seg * 8) = v;
	v_cvt_pk_bf16_f32 v48, v62, s0
	ds_write_b16 v128, v32 offset:12880
	v_cvt_pk_bf16_f32 v32, v46, s0
	ds_write_b16 v128, v16 offset:17424
	v_cvt_pk_bf16_f32 v16, v30, s0
	ds_write_b16 v128, v0 offset:17632
	v_cvt_pk_bf16_f32 v0, v15, s0
	s_ashr_i32 s11, s10, 31
	ds_write_b16 v128, v112 offset:3744
	v_cvt_pk_bf16_f32 v112, v127, s0
	ds_write_b16 v128, v96 offset:3808
	v_cvt_pk_bf16_f32 v96, v111, s0
	ds_write_b16 v128, v80 offset:8352
	v_cvt_pk_bf16_f32 v80, v95, s0
	ds_write_b16 v128, v64 offset:8416
	v_cvt_pk_bf16_f32 v64, v79, s0
	ds_write_b16 v128, v48 offset:12960
	v_cvt_pk_bf16_f32 v48, v63, s0
	ds_write_b16 v128, v32 offset:13024
	v_cvt_pk_bf16_f32 v32, v47, s0
	ds_write_b16 v128, v16 offset:17568
	v_cvt_pk_bf16_f32 v16, v31, s0
	ds_write_b16 v128, v0 offset:17776
	v_lshlrev_b32_e32 v0, 4, v149
	s_lshl_b64 s[10:11], s[10:11], 8
	ds_write_b16 v128, v112 offset:3888
	ds_write_b16 v128, v96 offset:3952
	ds_write_b16 v128, v80 offset:8496
	ds_write_b16 v128, v64 offset:8560
	ds_write_b16 v128, v48 offset:13104
	ds_write_b16 v128, v32 offset:13168
	ds_write_b16 v128, v16 offset:17712
	v_and_b32_e32 v128, 0x70, v0
	v_ashrrev_i32_e32 v6, 3, v149
	v_mov_b32_e32 v9, s11
	v_or_b32_e32 v8, s10, v134
	v_add_u32_e32 v10, v163, v128
	v_ashrrev_i32_e32 v7, 31, v6
	v_lshl_add_u32 v4, s14, 8, v145
	v_mad_u64_u32 v[0:1], s[10:11], v6, s13, v[10:11]
	v_lshl_add_u64 v[6:7], v[8:9], 0, v[6:7]
	v_readlane_b32 s16, v253, 39
	v_ashrrev_i32_e32 v5, 31, v4
	v_lshlrev_b64 v[6:7], 12, v[6:7]
	v_readlane_b32 s26, v253, 49
	v_readlane_b32 s27, v253, 50
	ds_read_b128 v[0:3], v0
	v_lshlrev_b64 v[12:13], 1, v[4:5]
	v_lshl_add_u64 v[6:7], s[26:27], 0, v[6:7]
	v_lshl_add_u64 v[4:5], v[6:7], 0, v[12:13]
	v_lshl_add_u64 v[14:15], v[4:5], 0, v[128:129]
	v_add_u32_e32 v4, 64, v149
	v_ashrrev_i32_e32 v16, 3, v4
	v_mad_u64_u32 v[4:5], s[10:11], v16, s13, v[10:11]
	v_ashrrev_i32_e32 v17, 31, v16
	ds_read_b128 v[4:7], v4
	s_waitcnt lgkmcnt(1)
	global_store_dwordx4 v[14:15], v[0:3], off sc1
	v_readlane_b32 s17, v253, 40
	v_readlane_b32 s18, v253, 41
	v_lshl_add_u64 v[0:1], v[8:9], 0, v[16:17]
	v_lshlrev_b64 v[0:1], 12, v[0:1]
	v_lshl_add_u64 v[0:1], s[26:27], 0, v[0:1]
	v_lshl_add_u64 v[0:1], v[0:1], 0, v[12:13]
	v_lshl_add_u64 v[0:1], v[0:1], 0, v[128:129]
	s_waitcnt lgkmcnt(0)
	global_store_dwordx4 v[0:1], v[4:7], off sc1
	v_add_u32_e32 v0, 0x80, v149
	v_readlane_b32 s19, v253, 42
	v_ashrrev_i32_e32 v4, 3, v0
	v_ashrrev_i32_e32 v5, 31, v4
	v_mad_u64_u32 v[0:1], s[10:11], v4, s13, v[10:11]
	v_lshl_add_u64 v[4:5], v[8:9], 0, v[4:5]
	v_lshlrev_b64 v[4:5], 12, v[4:5]
	ds_read_b128 v[0:3], v0
	v_lshl_add_u64 v[4:5], s[26:27], 0, v[4:5]
	v_lshl_add_u64 v[4:5], v[4:5], 0, v[12:13]
	v_lshl_add_u64 v[14:15], v[4:5], 0, v[128:129]
	v_add_u32_e32 v4, 0xc0, v149
	v_ashrrev_i32_e32 v16, 3, v4
	v_mad_u64_u32 v[4:5], s[10:11], v16, s13, v[10:11]
	v_ashrrev_i32_e32 v17, 31, v16
	ds_read_b128 v[4:7], v4
	s_waitcnt lgkmcnt(1)
	global_store_dwordx4 v[14:15], v[0:3], off sc1
	v_readlane_b32 s20, v253, 43
	v_readlane_b32 s21, v253, 44
	v_lshl_add_u64 v[0:1], v[8:9], 0, v[16:17]
	v_lshlrev_b64 v[0:1], 12, v[0:1]
	v_lshl_add_u64 v[0:1], s[26:27], 0, v[0:1]
	v_lshl_add_u64 v[0:1], v[0:1], 0, v[12:13]
	v_lshl_add_u64 v[0:1], v[0:1], 0, v[128:129]
	s_waitcnt lgkmcnt(0)
	global_store_dwordx4 v[0:1], v[4:7], off sc1
	v_add_u32_e32 v0, 0x100, v149
	v_readlane_b32 s22, v253, 45
	v_ashrrev_i32_e32 v4, 3, v0
	v_ashrrev_i32_e32 v5, 31, v4
	v_mad_u64_u32 v[0:1], s[10:11], v4, s13, v[10:11]
	v_lshl_add_u64 v[4:5], v[8:9], 0, v[4:5]
	v_lshlrev_b64 v[4:5], 12, v[4:5]
	ds_read_b128 v[0:3], v0
	v_lshl_add_u64 v[4:5], s[26:27], 0, v[4:5]
	v_lshl_add_u64 v[4:5], v[4:5], 0, v[12:13]
	v_lshl_add_u64 v[14:15], v[4:5], 0, v[128:129]
	v_add_u32_e32 v4, 0x140, v149
	v_ashrrev_i32_e32 v16, 3, v4
	v_mad_u64_u32 v[4:5], s[10:11], v16, s13, v[10:11]
	v_ashrrev_i32_e32 v17, 31, v16
	ds_read_b128 v[4:7], v4
	s_waitcnt lgkmcnt(1)
	global_store_dwordx4 v[14:15], v[0:3], off sc1
	v_readlane_b32 s23, v253, 46
	v_readlane_b32 s24, v253, 47
	v_lshl_add_u64 v[0:1], v[8:9], 0, v[16:17]
	v_lshlrev_b64 v[0:1], 12, v[0:1]
	v_lshl_add_u64 v[0:1], s[26:27], 0, v[0:1]
	v_lshl_add_u64 v[0:1], v[0:1], 0, v[12:13]
	v_lshl_add_u64 v[0:1], v[0:1], 0, v[128:129]
	s_waitcnt lgkmcnt(0)
	global_store_dwordx4 v[0:1], v[4:7], off sc1
	v_add_u32_e32 v0, 0x180, v149
	v_readlane_b32 s25, v253, 48
	v_ashrrev_i32_e32 v4, 3, v0
	v_ashrrev_i32_e32 v5, 31, v4
	v_mad_u64_u32 v[0:1], s[10:11], v4, s13, v[10:11]
	v_lshl_add_u64 v[4:5], v[8:9], 0, v[4:5]
	v_lshlrev_b64 v[4:5], 12, v[4:5]
	ds_read_b128 v[0:3], v0
	v_lshl_add_u64 v[4:5], s[26:27], 0, v[4:5]
	v_lshl_add_u64 v[4:5], v[4:5], 0, v[12:13]
	v_lshl_add_u64 v[14:15], v[4:5], 0, v[128:129]
	v_add_u32_e32 v4, 0x1c0, v149
	v_ashrrev_i32_e32 v16, 3, v4
	v_mad_u64_u32 v[4:5], s[10:11], v16, s13, v[10:11]
	v_ashrrev_i32_e32 v17, 31, v16
	ds_read_b128 v[4:7], v4
	s_waitcnt lgkmcnt(1)
; template <int EPI, int PN>
; __device__ void gemm_phase(const Params& p, const u16* __restrict__ A, const u16* __restrict__ Bt, int nNt, char* smem) {
;     ...
;   for (int q = jb;; q += NJ) {
;     const int pl = q / (4 * PN), w = q % (4 * PN);
;     const int gp = pl * 8 + xcd;
;     if (gp >= npatch) break;
;     const int mt = (gp / npn) * 4 + (w & 3), nt = (gp % npn) * PN + (w >> 2);
;     ...
; #pragma unroll
;       for (int it = 0; it < 16; ++it) {
;         const int c = it * 64 + laneE, row = c >> 3, seg = c & 7;
;         const uint4 v = *(const uint4*)(et + row * 144 + seg * 16);
;         if (EPI == 0) *(uint4*)(p.proj + (row0 + row) * NPROJ + col0 + seg * 8) = v;
;         else *(uint4*)(p.qp + (row0 + row) * DM + col0 + seg * 8) = v;
;       }
	global_store_dwordx4 v[14:15], v[0:3], off sc1
	v_readlane_b32 s28, v253, 51
	v_readlane_b32 s29, v253, 52
	v_lshl_add_u64 v[0:1], v[8:9], 0, v[16:17]
	v_lshlrev_b64 v[0:1], 12, v[0:1]
	v_lshl_add_u64 v[0:1], s[26:27], 0, v[0:1]
	v_lshl_add_u64 v[0:1], v[0:1], 0, v[12:13]
	v_lshl_add_u64 v[0:1], v[0:1], 0, v[128:129]
	s_waitcnt lgkmcnt(0)
	global_store_dwordx4 v[0:1], v[4:7], off sc1
	v_add_u32_e32 v0, 0x200, v149
	v_readlane_b32 s30, v253, 53
	v_ashrrev_i32_e32 v4, 3, v0
	v_ashrrev_i32_e32 v5, 31, v4
	v_mad_u64_u32 v[0:1], s[10:11], v4, s13, v[10:11]
	v_lshl_add_u64 v[4:5], v[8:9], 0, v[4:5]
	v_lshlrev_b64 v[4:5], 12, v[4:5]
	ds_read_b128 v[0:3], v0
	v_lshl_add_u64 v[4:5], s[26:27], 0, v[4:5]
	v_lshl_add_u64 v[4:5], v[4:5], 0, v[12:13]
	v_lshl_add_u64 v[14:15], v[4:5], 0, v[128:129]
	v_add_u32_e32 v4, 0x240, v149
	v_ashrrev_i32_e32 v16, 3, v4
	v_mad_u64_u32 v[4:5], s[10:11], v16, s13, v[10:11]
	v_ashrrev_i32_e32 v17, 31, v16
	ds_read_b128 v[4:7], v4
	s_waitcnt lgkmcnt(1)
	global_store_dwordx4 v[14:15], v[0:3], off sc1
	v_readlane_b32 s31, v253, 54
	s_nop 0
	v_lshl_add_u64 v[0:1], v[8:9], 0, v[16:17]
	v_lshlrev_b64 v[0:1], 12, v[0:1]
	v_lshl_add_u64 v[0:1], s[26:27], 0, v[0:1]
	v_lshl_add_u64 v[0:1], v[0:1], 0, v[12:13]
	v_lshl_add_u64 v[0:1], v[0:1], 0, v[128:129]
	s_waitcnt lgkmcnt(0)
	global_store_dwordx4 v[0:1], v[4:7], off sc1
	v_add_u32_e32 v0, 0x280, v149
	s_nop 0
	v_ashrrev_i32_e32 v4, 3, v0
	v_ashrrev_i32_e32 v5, 31, v4
	v_mad_u64_u32 v[0:1], s[10:11], v4, s13, v[10:11]
	v_lshl_add_u64 v[4:5], v[8:9], 0, v[4:5]
	v_lshlrev_b64 v[4:5], 12, v[4:5]
	ds_read_b128 v[0:3], v0
	v_lshl_add_u64 v[4:5], s[26:27], 0, v[4:5]
	v_lshl_add_u64 v[4:5], v[4:5], 0, v[12:13]
	v_lshl_add_u64 v[14:15], v[4:5], 0, v[128:129]
	v_add_u32_e32 v4, 0x2c0, v149
	v_ashrrev_i32_e32 v16, 3, v4
	v_mad_u64_u32 v[4:5], s[10:11], v16, s13, v[10:11]
	v_ashrrev_i32_e32 v17, 31, v16
	ds_read_b128 v[4:7], v4
	s_waitcnt lgkmcnt(1)
	global_store_dwordx4 v[14:15], v[0:3], off sc1
	s_nop 1
	v_lshl_add_u64 v[0:1], v[8:9], 0, v[16:17]
	v_lshlrev_b64 v[0:1], 12, v[0:1]
	v_lshl_add_u64 v[0:1], s[26:27], 0, v[0:1]
	v_lshl_add_u64 v[0:1], v[0:1], 0, v[12:13]
	v_lshl_add_u64 v[0:1], v[0:1], 0, v[128:129]
	s_waitcnt lgkmcnt(0)
	global_store_dwordx4 v[0:1], v[4:7], off sc1
	v_add_u32_e32 v0, 0x300, v149
	s_nop 0
	v_ashrrev_i32_e32 v4, 3, v0
	v_ashrrev_i32_e32 v5, 31, v4
	v_mad_u64_u32 v[0:1], s[10:11], v4, s13, v[10:11]
	v_lshl_add_u64 v[4:5], v[8:9], 0, v[4:5]
	v_lshlrev_b64 v[4:5], 12, v[4:5]
	ds_read_b128 v[0:3], v0
	v_lshl_add_u64 v[4:5], s[26:27], 0, v[4:5]
	v_lshl_add_u64 v[4:5], v[4:5], 0, v[12:13]
	v_lshl_add_u64 v[14:15], v[4:5], 0, v[128:129]
	v_add_u32_e32 v4, 0x340, v149
	v_ashrrev_i32_e32 v16, 3, v4
	v_mad_u64_u32 v[4:5], s[10:11], v16, s13, v[10:11]
	v_ashrrev_i32_e32 v17, 31, v16
	ds_read_b128 v[4:7], v4
	s_waitcnt lgkmcnt(1)
	global_store_dwordx4 v[14:15], v[0:3], off sc1
	s_nop 1
	v_lshl_add_u64 v[0:1], v[8:9], 0, v[16:17]
	v_lshlrev_b64 v[0:1], 12, v[0:1]
	v_lshl_add_u64 v[0:1], s[26:27], 0, v[0:1]
	v_lshl_add_u64 v[0:1], v[0:1], 0, v[12:13]
	v_lshl_add_u64 v[0:1], v[0:1], 0, v[128:129]
	s_waitcnt lgkmcnt(0)
	global_store_dwordx4 v[0:1], v[4:7], off sc1
	v_add_u32_e32 v0, 0x380, v149
	s_nop 0
	v_ashrrev_i32_e32 v4, 3, v0
	v_ashrrev_i32_e32 v5, 31, v4
	v_mad_u64_u32 v[0:1], s[10:11], v4, s13, v[10:11]
	v_lshl_add_u64 v[4:5], v[8:9], 0, v[4:5]
	v_lshlrev_b64 v[4:5], 12, v[4:5]
	v_lshl_add_u64 v[4:5], s[26:27], 0, v[4:5]
	v_lshl_add_u64 v[4:5], v[4:5], 0, v[12:13]
	v_lshl_add_u64 v[14:15], v[4:5], 0, v[128:129]
	v_add_u32_e32 v4, 0x3c0, v149
	v_ashrrev_i32_e32 v16, 3, v4
	ds_read_b128 v[0:3], v0
	v_mad_u64_u32 v[4:5], s[10:11], v16, s13, v[10:11]
	v_readlane_b32 s10, v254, 28
	s_add_i32 s34, s34, s10
	s_ashr_i32 s10, s34, 31
	v_ashrrev_i32_e32 v17, 31, v16
	s_lshr_b32 s10, s10, 27
	ds_read_b128 v[4:7], v4
	s_waitcnt lgkmcnt(1)
	global_store_dwordx4 v[14:15], v[0:3], off sc1
	s_add_i32 s10, s34, s10
	s_ashr_i32 s10, s10, 5
	v_lshl_add_u64 v[0:1], v[8:9], 0, v[16:17]
	v_lshlrev_b64 v[0:1], 12, v[0:1]
	v_lshl_add_u64 v[0:1], s[26:27], 0, v[0:1]
	s_lshl_b32 s10, s10, 3
	v_readlane_b32 s11, v254, 24
	v_lshl_add_u64 v[0:1], v[0:1], 0, v[12:13]
	s_or_b32 s11, s10, s11
	v_lshl_add_u64 v[0:1], v[0:1], 0, v[128:129]
	s_cmp_gt_i32 s11, 31
	s_waitcnt lgkmcnt(0)
	global_store_dwordx4 v[0:1], v[4:7], off sc1
	s_waitcnt vmcnt(63) expcnt(7) lgkmcnt(15)
	s_barrier
	s_cbranch_scc0 .LBB0_722
